# 16384 w_ffn_out transpose items moved from phase 4 (both loop bounds) to the FFN-in tail of WGs 128..255, unrolled with 2-deep load prefetch (on v44)
# speedup vs baseline: 1.0038x; 1.0038x over previous
.LBB0_464:
	s_min_i32 s5, s84, 0x80
	v_readlane_b32 s0, v254, 0
	s_waitcnt vmcnt(0)
	v_lshrrev_b32_e32 v2, 6, v0
	s_mov_b32 s2, s0
	s_cmp_ge_i32 s0, s5
	s_mul_i32 s0, s0, 2
	v_add3_u32 v3, v2, s0, -1
	s_cselect_b64 vcc, -1, 0
	s_sub_i32 s0, s2, s5
	s_mul_i32 s4, s5, 2
	s_lshl_b32 s0, s0, 3
	s_add_i32 s0, s0, s4
	v_readlane_b32 s1, v254, 1
	v_add_u32_e32 v2, s0, v2
	v_add_u32_e32 v31, -64, v0
	s_movk_i32 s7, 0x80
	v_cmp_gt_u32_e64 s[0:1], s7, v31
	v_cndmask_b32_e32 v30, v3, v2, vcc
	s_mov_b32 s6, 0x14200
	s_or_b64 s[0:1], vcc, s[0:1]
	v_cmp_gt_i32_e32 vcc, s6, v30
	s_movk_i32 s3, 0x80
	s_and_b64 s[6:7], s[0:1], vcc
	s_and_saveexec_b64 s[0:1], s[6:7]
	s_cbranch_execz .LBB0_491
	s_sub_i32 s5, s84, s5
	v_lshlrev_b32_e32 v2, 8, v0
	s_lshl_b32 s33, s5, 3
	v_and_b32_e32 v2, 0x1c000, v2
	s_add_i32 s33, s33, s4
	v_add_u32_e32 v7, 0, v2
	v_lshlrev_b32_e32 v2, 4, v0
	v_and_b32_e32 v24, 0x70, v2
	v_lshlrev_b32_e32 v2, 3, v0
	s_add_u32 s6, s66, 0x8100000
	v_and_b32_e32 v2, 56, v2
	s_addc_u32 s7, s67, 0
	v_mul_u32_u24_e32 v6, 0x84, v2
	v_lshlrev_b32_e32 v2, 1, v2
	v_mov_b32_e32 v3, 0
	s_add_u32 s8, s66, 0x93400
	v_lshl_add_u64 v[12:13], s[66:67], 0, v[2:3]
	s_addc_u32 s9, s67, 0
	s_mov_b64 s[12:13], 0x6100000
	s_add_u32 s10, s66, 0xbc000
	v_lshl_add_u64 v[8:9], v[12:13], 0, s[12:13]
	s_mov_b64 s[12:13], 0x5100000
	s_mov_b64 s[4:5], 0x12d00000
	s_addc_u32 s11, s67, 0
	v_lshl_add_u64 v[10:11], v[12:13], 0, s[12:13]
	s_mov_b64 s[12:13], 0x4100000
	v_lshl_add_u64 v[4:5], v[12:13], 0, s[4:5]
	v_lshl_add_u64 v[12:13], v[12:13], 0, s[12:13]
	s_add_u32 s12, s66, 0x100000
	s_addc_u32 s13, s67, 0
	v_readlane_b32 s36, v254, 20
	v_lshrrev_b32_e32 v31, 3, v1
	s_add_u32 s14, s66, 0x8b400
	v_readlane_b32 s40, v254, 24
	v_readlane_b32 s41, v254, 25
	v_add_u32_e32 v26, v7, v24
	v_mul_u32_u24_e32 v27, 0x84, v31
	s_addc_u32 s15, s67, 0
	v_readlane_b32 s42, v254, 26
	v_readlane_b32 s43, v254, 27
	v_readlane_b32 s44, v254, 28
	v_readlane_b32 s45, v254, 29
	v_readlane_b32 s46, v254, 30
	v_readlane_b32 s47, v254, 31
	v_readlane_b32 s48, v254, 32
	v_readlane_b32 s49, v254, 33
	v_readlane_b32 s50, v254, 34
	v_readlane_b32 s51, v254, 35
	s_mov_b64 s[20:21], s[40:41]
	v_lshlrev_b32_e32 v2, 2, v31
	v_lshrrev_b32_e32 v1, 1, v1
	v_and_b32_e32 v40, 1, v0
	s_add_u32 s16, s66, 0xb4000
	v_mov_b32_e32 v25, v3
	v_readlane_b32 s37, v254, 21
	v_readlane_b32 s38, v254, 22
	v_readlane_b32 s39, v254, 23
	s_mov_b64 s[24:25], s[44:45]
	s_mov_b64 s[26:27], s[46:47]
	s_mov_b64 s[28:29], s[48:49]
	s_mov_b64 s[30:31], s[50:51]
	v_add_u32_e32 v44, v26, v27
	v_or_b32_e32 v32, 8, v31
	v_or_b32_e32 v33, 16, v31
	v_or_b32_e32 v34, 24, v31
	v_or_b32_e32 v35, 32, v31
	v_or_b32_e32 v36, 40, v31
	v_or_b32_e32 v37, 48, v31
	v_or_b32_e32 v38, 56, v31
	v_add3_u32 v39, v7, v6, v2
	v_lshlrev_b32_e32 v6, 5, v40
	v_lshl_add_u32 v41, v1, 2, v7
	v_mul_u32_u24_e32 v42, 0x1080, v40
	v_mov_b32_e32 v7, v3
	v_cmp_eq_u32_e64 s[4:5], 0, v40
	s_addc_u32 s17, s67, 0
	v_lshl_add_u64 v[14:15], s[60:61], 0, v[24:25]
	v_lshl_add_u64 v[16:17], s[54:55], 0, v[24:25]
	s_mov_b64 s[22:23], s[42:43]
	v_lshl_add_u64 v[18:19], s[30:31], 0, v[24:25]
	v_lshl_add_u64 v[20:21], s[26:27], 0, v[24:25]
	v_lshl_add_u64 v[22:23], s[24:25], 0, v[24:25]
	v_lshl_add_u64 v[24:25], s[28:29], 0, v[24:25]
	v_lshlrev_b32_e32 v43, 5, v30
	s_lshl_b32 s34, s33, 5
	s_mov_b64 s[18:19], 0
	s_movk_i32 s35, 0x3fff
	s_movk_i32 s36, 0x4fff
	s_movk_i32 s37, 0x5fff
	s_movk_i32 s38, 0x7fff
	s_mov_b32 s39, 0x12bff
	v_add_u32_e32 v45, 0x420, v44
	v_add_u32_e32 v46, 0x428, v44
	v_add_u32_e32 v47, 0x840, v44
	v_add_u32_e32 v48, 0x848, v44
	v_add_u32_e32 v49, 0xc60, v44
	v_add_u32_e32 v50, 0xc68, v44
	s_mov_b32 s40, 0xffff0000
	s_mov_b32 s41, 0xbe83
	s_movk_i32 s42, 0x2b0
	s_movk_i32 s43, 0x2a80
	s_mov_b32 s44, 0x42fe0000
	s_mov_b32 s45, 0xc0c0500
	s_mov_b32 s46, 0x141ff
	v_add_u32_e32 v51, 0x1080, v44
	v_add_u32_e32 v52, 0x1088, v44
	v_add_u32_e32 v53, 0x14a0, v44
	v_add_u32_e32 v54, 0x14a8, v44
	v_add_u32_e32 v55, 0x18c0, v44
	s_branch .LBB0_468

.LBB0_1906:
	s_waitcnt vmcnt(0)
	s_mov_b32 s2, s86
	s_barrier
	v_readlane_b32 s94, v254, 0
	s_nop 3
	s_cmpk_lt_u32 s94, 0x80
	s_cbranch_scc1 .Lwf_done
	v_readlane_b32 s96, v254, 2
	v_readlane_b32 s97, v254, 3
	v_readfirstlane_b32 s95, v0
	s_nop 3
	s_sub_u32 s96, s96, 0x28
	s_subb_u32 s97, s97, 0
	s_load_dwordx2 s[100:101], s[96:97], 0x0
	s_lshr_b32 s95, s95, 6
	s_sub_u32 s94, s94, 0x80
	s_lshl_b32 s94, s94, 3
	s_add_u32 s94, s94, s95
	s_add_u32 s94, s94, 0x1600
	v_and_b32_e32 v2, 63, v0
	v_lshrrev_b32_e32 v3, 3, v2
	v_and_b32_e32 v4, 7, v2
	v_lshlrev_b32_e32 v5, 14, v3
	v_lshl_add_u32 v5, v4, 4, v5
	v_add_u32_e32 v6, 0x0, v5
	v_add_u32_e32 v7, 0x20000, v5
	v_add_u32_e32 v8, 0x40000, v5
	v_add_u32_e32 v9, 0x60000, v5
	v_add_u32_e32 v10, 0x80000, v5
	v_add_u32_e32 v11, 0xa0000, v5
	v_add_u32_e32 v12, 0xc0000, v5
	v_add_u32_e32 v13, 0xe0000, v5
	s_lshl_b32 s95, s95, 14
	v_mul_u32_u24_e32 v14, 0x84, v3
	v_lshl_add_u32 v14, v4, 4, v14
	v_add_u32_e32 v14, s95, v14
	v_mul_u32_u24_e32 v15, 0x420, v4
	v_lshl_add_u32 v15, v3, 2, v15
	v_add_u32_e32 v15, s95, v15
	v_mul_u32_u24_e32 v16, 0x5600, v3
	v_lshl_add_u32 v16, v4, 4, v16
	v_add_u32_e32 v17, 0x2b000, v16
	v_add_u32_e32 v18, 0x56000, v16
	v_add_u32_e32 v19, 0x81000, v16
	s_waitcnt lgkmcnt(0)
	s_mov_b32 s95, s94
	s_lshr_b32 vcc_lo, s95, 7
	s_and_b32 vcc_hi, s95, 0x7f
	s_lshl_b32 vcc_lo, vcc_lo, 20
	s_lshl_b32 vcc_hi, vcc_hi, 7
	s_add_u32 s96, s100, vcc_lo
	s_addc_u32 s97, s101, 0
	s_add_u32 s96, s96, vcc_hi
	s_addc_u32 s97, s97, 0
	global_load_dwordx4 v[20:23], v6, s[96:97]
	global_load_dwordx4 v[24:27], v7, s[96:97]
	global_load_dwordx4 v[28:31], v8, s[96:97]
	global_load_dwordx4 v[32:35], v9, s[96:97]
	global_load_dwordx4 v[36:39], v10, s[96:97]
	global_load_dwordx4 v[40:43], v11, s[96:97]
	global_load_dwordx4 v[44:47], v12, s[96:97]
	global_load_dwordx4 v[48:51], v13, s[96:97]
	s_add_u32 s95, s94, 0x400
	s_lshr_b32 vcc_lo, s95, 7
	s_and_b32 vcc_hi, s95, 0x7f
	s_lshl_b32 vcc_lo, vcc_lo, 20
	s_lshl_b32 vcc_hi, vcc_hi, 7
	s_add_u32 s96, s100, vcc_lo
	s_addc_u32 s97, s101, 0
	s_add_u32 s96, s96, vcc_hi
	s_addc_u32 s97, s97, 0
	global_load_dwordx4 v[100:103], v6, s[96:97]
	global_load_dwordx4 v[104:107], v7, s[96:97]
	global_load_dwordx4 v[108:111], v8, s[96:97]
	global_load_dwordx4 v[112:115], v9, s[96:97]
	global_load_dwordx4 v[116:119], v10, s[96:97]
	global_load_dwordx4 v[120:123], v11, s[96:97]
	global_load_dwordx4 v[124:127], v12, s[96:97]
	global_load_dwordx4 v[128:131], v13, s[96:97]
	s_waitcnt vmcnt(15)
	ds_write_b32 v14, v20 offset:0
	ds_write_b32 v14, v21 offset:4
	ds_write_b32 v14, v22 offset:8
	ds_write_b32 v14, v23 offset:12
	s_waitcnt vmcnt(14)
	ds_write_b32 v14, v24 offset:1056
	ds_write_b32 v14, v25 offset:1060
	ds_write_b32 v14, v26 offset:1064
	ds_write_b32 v14, v27 offset:1068
	s_waitcnt vmcnt(13)
	ds_write_b32 v14, v28 offset:2112
	ds_write_b32 v14, v29 offset:2116
	ds_write_b32 v14, v30 offset:2120
	ds_write_b32 v14, v31 offset:2124
	s_waitcnt vmcnt(12)
	ds_write_b32 v14, v32 offset:3168
	ds_write_b32 v14, v33 offset:3172
	ds_write_b32 v14, v34 offset:3176
	ds_write_b32 v14, v35 offset:3180
	s_waitcnt vmcnt(11)
	ds_write_b32 v14, v36 offset:4224
	ds_write_b32 v14, v37 offset:4228
	ds_write_b32 v14, v38 offset:4232
	ds_write_b32 v14, v39 offset:4236
	s_waitcnt vmcnt(10)
	ds_write_b32 v14, v40 offset:5280
	ds_write_b32 v14, v41 offset:5284
	ds_write_b32 v14, v42 offset:5288
	ds_write_b32 v14, v43 offset:5292
	s_waitcnt vmcnt(9)
	ds_write_b32 v14, v44 offset:6336
	ds_write_b32 v14, v45 offset:6340
	ds_write_b32 v14, v46 offset:6344
	ds_write_b32 v14, v47 offset:6348
	s_waitcnt vmcnt(8)
	ds_write_b32 v14, v48 offset:7392
	ds_write_b32 v14, v49 offset:7396
	ds_write_b32 v14, v50 offset:7400
	ds_write_b32 v14, v51 offset:7404
	s_add_u32 s95, s94, 0x800
	s_lshr_b32 vcc_lo, s95, 7
	s_and_b32 vcc_hi, s95, 0x7f
	s_lshl_b32 vcc_lo, vcc_lo, 20
	s_lshl_b32 vcc_hi, vcc_hi, 7
	s_add_u32 s96, s100, vcc_lo
	s_addc_u32 s97, s101, 0
	s_add_u32 s96, s96, vcc_hi
	s_addc_u32 s97, s97, 0
	global_load_dwordx4 v[20:23], v6, s[96:97]
	global_load_dwordx4 v[24:27], v7, s[96:97]
	global_load_dwordx4 v[28:31], v8, s[96:97]
	global_load_dwordx4 v[32:35], v9, s[96:97]
	global_load_dwordx4 v[36:39], v10, s[96:97]
	global_load_dwordx4 v[40:43], v11, s[96:97]
	global_load_dwordx4 v[44:47], v12, s[96:97]
	global_load_dwordx4 v[48:51], v13, s[96:97]
	ds_read2_b32 v[52:53], v15 offset0:0 offset1:33
	ds_read2_b32 v[54:55], v15 offset0:66 offset1:99
	ds_read2_b32 v[56:57], v15 offset0:132 offset1:165
	ds_read2_b32 v[58:59], v15 offset0:198 offset1:231
	ds_read2_b32 v[60:61], v15 offset0:8 offset1:41
	ds_read2_b32 v[62:63], v15 offset0:74 offset1:107
	ds_read2_b32 v[64:65], v15 offset0:140 offset1:173
	ds_read2_b32 v[66:67], v15 offset0:206 offset1:239
	ds_read2_b32 v[68:69], v15 offset0:16 offset1:49
	ds_read2_b32 v[70:71], v15 offset0:82 offset1:115
	ds_read2_b32 v[72:73], v15 offset0:148 offset1:181
	ds_read2_b32 v[74:75], v15 offset0:214 offset1:247
	ds_read2_b32 v[76:77], v15 offset0:24 offset1:57
	ds_read2_b32 v[78:79], v15 offset0:90 offset1:123
	ds_read2_b32 v[80:81], v15 offset0:156 offset1:189
	ds_read2_b32 v[82:83], v15 offset0:222 offset1:255
	s_mov_b32 s95, s94
	s_lshr_b32 vcc_lo, s95, 7
	s_and_b32 vcc_hi, s95, 0x7f
	s_mul_i32 vcc_hi, vcc_hi, 0xac000
	s_lshl_b32 vcc_lo, vcc_lo, 7
	s_add_u32 s98, s66, 0x12d00000
	s_addc_u32 s99, s67, 0
	s_add_u32 s98, s98, vcc_hi
	s_addc_u32 s99, s99, 0
	s_add_u32 s98, s98, vcc_lo
	s_addc_u32 s99, s99, 0
	s_waitcnt lgkmcnt(0)
	v_cvt_pk_bf16_f32 v84, v52, v53
	v_cvt_pk_bf16_f32 v85, v54, v55
	v_cvt_pk_bf16_f32 v86, v56, v57
	v_cvt_pk_bf16_f32 v87, v58, v59
	v_cvt_pk_bf16_f32 v88, v60, v61
	v_cvt_pk_bf16_f32 v89, v62, v63
	v_cvt_pk_bf16_f32 v90, v64, v65
	v_cvt_pk_bf16_f32 v91, v66, v67
	v_cvt_pk_bf16_f32 v92, v68, v69
	v_cvt_pk_bf16_f32 v93, v70, v71
	v_cvt_pk_bf16_f32 v94, v72, v73
	v_cvt_pk_bf16_f32 v95, v74, v75
	v_cvt_pk_bf16_f32 v96, v76, v77
	v_cvt_pk_bf16_f32 v97, v78, v79
	v_cvt_pk_bf16_f32 v98, v80, v81
	v_cvt_pk_bf16_f32 v99, v82, v83
	global_store_dwordx4 v16, v[84:87], s[98:99]
	global_store_dwordx4 v17, v[88:91], s[98:99]
	global_store_dwordx4 v18, v[92:95], s[98:99]
	global_store_dwordx4 v19, v[96:99], s[98:99]
	s_waitcnt vmcnt(19)
	ds_write_b32 v14, v100 offset:0
	ds_write_b32 v14, v101 offset:4
	ds_write_b32 v14, v102 offset:8
	ds_write_b32 v14, v103 offset:12
	s_waitcnt vmcnt(18)
	ds_write_b32 v14, v104 offset:1056
	ds_write_b32 v14, v105 offset:1060
	ds_write_b32 v14, v106 offset:1064
	ds_write_b32 v14, v107 offset:1068
	s_waitcnt vmcnt(17)
	ds_write_b32 v14, v108 offset:2112
	ds_write_b32 v14, v109 offset:2116
	ds_write_b32 v14, v110 offset:2120
	ds_write_b32 v14, v111 offset:2124
	s_waitcnt vmcnt(16)
	ds_write_b32 v14, v112 offset:3168
	ds_write_b32 v14, v113 offset:3172
	ds_write_b32 v14, v114 offset:3176
	ds_write_b32 v14, v115 offset:3180
	s_waitcnt vmcnt(15)
	ds_write_b32 v14, v116 offset:4224
	ds_write_b32 v14, v117 offset:4228
	ds_write_b32 v14, v118 offset:4232
	ds_write_b32 v14, v119 offset:4236
	s_waitcnt vmcnt(14)
	ds_write_b32 v14, v120 offset:5280
	ds_write_b32 v14, v121 offset:5284
	ds_write_b32 v14, v122 offset:5288
	ds_write_b32 v14, v123 offset:5292
	s_waitcnt vmcnt(13)
	ds_write_b32 v14, v124 offset:6336
	ds_write_b32 v14, v125 offset:6340
	ds_write_b32 v14, v126 offset:6344
	ds_write_b32 v14, v127 offset:6348
	s_waitcnt vmcnt(12)
	ds_write_b32 v14, v128 offset:7392
	ds_write_b32 v14, v129 offset:7396
	ds_write_b32 v14, v130 offset:7400
	ds_write_b32 v14, v131 offset:7404
	s_add_u32 s95, s94, 0xc00
	s_lshr_b32 vcc_lo, s95, 7
	s_and_b32 vcc_hi, s95, 0x7f
	s_lshl_b32 vcc_lo, vcc_lo, 20
	s_lshl_b32 vcc_hi, vcc_hi, 7
	s_add_u32 s96, s100, vcc_lo
	s_addc_u32 s97, s101, 0
	s_add_u32 s96, s96, vcc_hi
	s_addc_u32 s97, s97, 0
	global_load_dwordx4 v[100:103], v6, s[96:97]
	global_load_dwordx4 v[104:107], v7, s[96:97]
	global_load_dwordx4 v[108:111], v8, s[96:97]
	global_load_dwordx4 v[112:115], v9, s[96:97]
	global_load_dwordx4 v[116:119], v10, s[96:97]
	global_load_dwordx4 v[120:123], v11, s[96:97]
	global_load_dwordx4 v[124:127], v12, s[96:97]
	global_load_dwordx4 v[128:131], v13, s[96:97]
	ds_read2_b32 v[52:53], v15 offset0:0 offset1:33
	ds_read2_b32 v[54:55], v15 offset0:66 offset1:99
	ds_read2_b32 v[56:57], v15 offset0:132 offset1:165
	ds_read2_b32 v[58:59], v15 offset0:198 offset1:231
	ds_read2_b32 v[60:61], v15 offset0:8 offset1:41
	ds_read2_b32 v[62:63], v15 offset0:74 offset1:107
	ds_read2_b32 v[64:65], v15 offset0:140 offset1:173
	ds_read2_b32 v[66:67], v15 offset0:206 offset1:239
	ds_read2_b32 v[68:69], v15 offset0:16 offset1:49
	ds_read2_b32 v[70:71], v15 offset0:82 offset1:115
	ds_read2_b32 v[72:73], v15 offset0:148 offset1:181
	ds_read2_b32 v[74:75], v15 offset0:214 offset1:247
	ds_read2_b32 v[76:77], v15 offset0:24 offset1:57
	ds_read2_b32 v[78:79], v15 offset0:90 offset1:123
	ds_read2_b32 v[80:81], v15 offset0:156 offset1:189
	ds_read2_b32 v[82:83], v15 offset0:222 offset1:255
	s_add_u32 s95, s94, 0x400
	s_lshr_b32 vcc_lo, s95, 7
	s_and_b32 vcc_hi, s95, 0x7f
	s_mul_i32 vcc_hi, vcc_hi, 0xac000
	s_lshl_b32 vcc_lo, vcc_lo, 7
	s_add_u32 s98, s66, 0x12d00000
	s_addc_u32 s99, s67, 0
	s_add_u32 s98, s98, vcc_hi
	s_addc_u32 s99, s99, 0
	s_add_u32 s98, s98, vcc_lo
	s_addc_u32 s99, s99, 0
	s_waitcnt lgkmcnt(0)
	v_cvt_pk_bf16_f32 v84, v52, v53
	v_cvt_pk_bf16_f32 v85, v54, v55
	v_cvt_pk_bf16_f32 v86, v56, v57
	v_cvt_pk_bf16_f32 v87, v58, v59
	v_cvt_pk_bf16_f32 v88, v60, v61
	v_cvt_pk_bf16_f32 v89, v62, v63
	v_cvt_pk_bf16_f32 v90, v64, v65
	v_cvt_pk_bf16_f32 v91, v66, v67
	v_cvt_pk_bf16_f32 v92, v68, v69
	v_cvt_pk_bf16_f32 v93, v70, v71
	v_cvt_pk_bf16_f32 v94, v72, v73
	v_cvt_pk_bf16_f32 v95, v74, v75
	v_cvt_pk_bf16_f32 v96, v76, v77
	v_cvt_pk_bf16_f32 v97, v78, v79
	v_cvt_pk_bf16_f32 v98, v80, v81
	v_cvt_pk_bf16_f32 v99, v82, v83
	global_store_dwordx4 v16, v[84:87], s[98:99]
	global_store_dwordx4 v17, v[88:91], s[98:99]
	global_store_dwordx4 v18, v[92:95], s[98:99]
	global_store_dwordx4 v19, v[96:99], s[98:99]
	s_waitcnt vmcnt(23)
	ds_write_b32 v14, v20 offset:0
	ds_write_b32 v14, v21 offset:4
	ds_write_b32 v14, v22 offset:8
	ds_write_b32 v14, v23 offset:12
	s_waitcnt vmcnt(22)
	ds_write_b32 v14, v24 offset:1056
	ds_write_b32 v14, v25 offset:1060
	ds_write_b32 v14, v26 offset:1064
	ds_write_b32 v14, v27 offset:1068
	s_waitcnt vmcnt(21)
	ds_write_b32 v14, v28 offset:2112
	ds_write_b32 v14, v29 offset:2116
	ds_write_b32 v14, v30 offset:2120
	ds_write_b32 v14, v31 offset:2124
	s_waitcnt vmcnt(20)
	ds_write_b32 v14, v32 offset:3168
	ds_write_b32 v14, v33 offset:3172
	ds_write_b32 v14, v34 offset:3176
	ds_write_b32 v14, v35 offset:3180
	s_waitcnt vmcnt(19)
	ds_write_b32 v14, v36 offset:4224
	ds_write_b32 v14, v37 offset:4228
	ds_write_b32 v14, v38 offset:4232
	ds_write_b32 v14, v39 offset:4236
	s_waitcnt vmcnt(18)
	ds_write_b32 v14, v40 offset:5280
	ds_write_b32 v14, v41 offset:5284
	ds_write_b32 v14, v42 offset:5288
	ds_write_b32 v14, v43 offset:5292
	s_waitcnt vmcnt(17)
	ds_write_b32 v14, v44 offset:6336
	ds_write_b32 v14, v45 offset:6340
	ds_write_b32 v14, v46 offset:6344
	ds_write_b32 v14, v47 offset:6348
	s_waitcnt vmcnt(16)
	ds_write_b32 v14, v48 offset:7392
	ds_write_b32 v14, v49 offset:7396
	ds_write_b32 v14, v50 offset:7400
	ds_write_b32 v14, v51 offset:7404
	s_add_u32 s95, s94, 0x1000
	s_lshr_b32 vcc_lo, s95, 7
	s_and_b32 vcc_hi, s95, 0x7f
	s_lshl_b32 vcc_lo, vcc_lo, 20
	s_lshl_b32 vcc_hi, vcc_hi, 7
	s_add_u32 s96, s100, vcc_lo
	s_addc_u32 s97, s101, 0
	s_add_u32 s96, s96, vcc_hi
	s_addc_u32 s97, s97, 0
	global_load_dwordx4 v[20:23], v6, s[96:97]
	global_load_dwordx4 v[24:27], v7, s[96:97]
	global_load_dwordx4 v[28:31], v8, s[96:97]
	global_load_dwordx4 v[32:35], v9, s[96:97]
	global_load_dwordx4 v[36:39], v10, s[96:97]
	global_load_dwordx4 v[40:43], v11, s[96:97]
	global_load_dwordx4 v[44:47], v12, s[96:97]
	global_load_dwordx4 v[48:51], v13, s[96:97]
	ds_read2_b32 v[52:53], v15 offset0:0 offset1:33
	ds_read2_b32 v[54:55], v15 offset0:66 offset1:99
	ds_read2_b32 v[56:57], v15 offset0:132 offset1:165
	ds_read2_b32 v[58:59], v15 offset0:198 offset1:231
	ds_read2_b32 v[60:61], v15 offset0:8 offset1:41
	ds_read2_b32 v[62:63], v15 offset0:74 offset1:107
	ds_read2_b32 v[64:65], v15 offset0:140 offset1:173
	ds_read2_b32 v[66:67], v15 offset0:206 offset1:239
	ds_read2_b32 v[68:69], v15 offset0:16 offset1:49
	ds_read2_b32 v[70:71], v15 offset0:82 offset1:115
	ds_read2_b32 v[72:73], v15 offset0:148 offset1:181
	ds_read2_b32 v[74:75], v15 offset0:214 offset1:247
	ds_read2_b32 v[76:77], v15 offset0:24 offset1:57
	ds_read2_b32 v[78:79], v15 offset0:90 offset1:123
	ds_read2_b32 v[80:81], v15 offset0:156 offset1:189
	ds_read2_b32 v[82:83], v15 offset0:222 offset1:255
	s_add_u32 s95, s94, 0x800
	s_lshr_b32 vcc_lo, s95, 7
	s_and_b32 vcc_hi, s95, 0x7f
	s_mul_i32 vcc_hi, vcc_hi, 0xac000
	s_lshl_b32 vcc_lo, vcc_lo, 7
	s_add_u32 s98, s66, 0x12d00000
	s_addc_u32 s99, s67, 0
	s_add_u32 s98, s98, vcc_hi
	s_addc_u32 s99, s99, 0
	s_add_u32 s98, s98, vcc_lo
	s_addc_u32 s99, s99, 0
	s_waitcnt lgkmcnt(0)
	v_cvt_pk_bf16_f32 v84, v52, v53
	v_cvt_pk_bf16_f32 v85, v54, v55
	v_cvt_pk_bf16_f32 v86, v56, v57
	v_cvt_pk_bf16_f32 v87, v58, v59
	v_cvt_pk_bf16_f32 v88, v60, v61
	v_cvt_pk_bf16_f32 v89, v62, v63
	v_cvt_pk_bf16_f32 v90, v64, v65
	v_cvt_pk_bf16_f32 v91, v66, v67
	v_cvt_pk_bf16_f32 v92, v68, v69
	v_cvt_pk_bf16_f32 v93, v70, v71
	v_cvt_pk_bf16_f32 v94, v72, v73
	v_cvt_pk_bf16_f32 v95, v74, v75
	v_cvt_pk_bf16_f32 v96, v76, v77
	v_cvt_pk_bf16_f32 v97, v78, v79
	v_cvt_pk_bf16_f32 v98, v80, v81
	v_cvt_pk_bf16_f32 v99, v82, v83
	global_store_dwordx4 v16, v[84:87], s[98:99]
	global_store_dwordx4 v17, v[88:91], s[98:99]
	global_store_dwordx4 v18, v[92:95], s[98:99]
	global_store_dwordx4 v19, v[96:99], s[98:99]
	s_waitcnt vmcnt(23)
	ds_write_b32 v14, v100 offset:0
	ds_write_b32 v14, v101 offset:4
	ds_write_b32 v14, v102 offset:8
	ds_write_b32 v14, v103 offset:12
	s_waitcnt vmcnt(22)
	ds_write_b32 v14, v104 offset:1056
	ds_write_b32 v14, v105 offset:1060
	ds_write_b32 v14, v106 offset:1064
	ds_write_b32 v14, v107 offset:1068
	s_waitcnt vmcnt(21)
	ds_write_b32 v14, v108 offset:2112
	ds_write_b32 v14, v109 offset:2116
	ds_write_b32 v14, v110 offset:2120
	ds_write_b32 v14, v111 offset:2124
	s_waitcnt vmcnt(20)
	ds_write_b32 v14, v112 offset:3168
	ds_write_b32 v14, v113 offset:3172
	ds_write_b32 v14, v114 offset:3176
	ds_write_b32 v14, v115 offset:3180
	s_waitcnt vmcnt(19)
	ds_write_b32 v14, v116 offset:4224
	ds_write_b32 v14, v117 offset:4228
	ds_write_b32 v14, v118 offset:4232
	ds_write_b32 v14, v119 offset:4236
	s_waitcnt vmcnt(18)
	ds_write_b32 v14, v120 offset:5280
	ds_write_b32 v14, v121 offset:5284
	ds_write_b32 v14, v122 offset:5288
	ds_write_b32 v14, v123 offset:5292
	s_waitcnt vmcnt(17)
	ds_write_b32 v14, v124 offset:6336
	ds_write_b32 v14, v125 offset:6340
	ds_write_b32 v14, v126 offset:6344
	ds_write_b32 v14, v127 offset:6348
	s_waitcnt vmcnt(16)
	ds_write_b32 v14, v128 offset:7392
	ds_write_b32 v14, v129 offset:7396
	ds_write_b32 v14, v130 offset:7400
	ds_write_b32 v14, v131 offset:7404
	s_add_u32 s95, s94, 0x1400
	s_lshr_b32 vcc_lo, s95, 7
	s_and_b32 vcc_hi, s95, 0x7f
	s_lshl_b32 vcc_lo, vcc_lo, 20
	s_lshl_b32 vcc_hi, vcc_hi, 7
	s_add_u32 s96, s100, vcc_lo
	s_addc_u32 s97, s101, 0
	s_add_u32 s96, s96, vcc_hi
	s_addc_u32 s97, s97, 0
	global_load_dwordx4 v[100:103], v6, s[96:97]
	global_load_dwordx4 v[104:107], v7, s[96:97]
	global_load_dwordx4 v[108:111], v8, s[96:97]
	global_load_dwordx4 v[112:115], v9, s[96:97]
	global_load_dwordx4 v[116:119], v10, s[96:97]
	global_load_dwordx4 v[120:123], v11, s[96:97]
	global_load_dwordx4 v[124:127], v12, s[96:97]
	global_load_dwordx4 v[128:131], v13, s[96:97]
	ds_read2_b32 v[52:53], v15 offset0:0 offset1:33
	ds_read2_b32 v[54:55], v15 offset0:66 offset1:99
	ds_read2_b32 v[56:57], v15 offset0:132 offset1:165
	ds_read2_b32 v[58:59], v15 offset0:198 offset1:231
	ds_read2_b32 v[60:61], v15 offset0:8 offset1:41
	ds_read2_b32 v[62:63], v15 offset0:74 offset1:107
	ds_read2_b32 v[64:65], v15 offset0:140 offset1:173
	ds_read2_b32 v[66:67], v15 offset0:206 offset1:239
	ds_read2_b32 v[68:69], v15 offset0:16 offset1:49
	ds_read2_b32 v[70:71], v15 offset0:82 offset1:115
	ds_read2_b32 v[72:73], v15 offset0:148 offset1:181
	ds_read2_b32 v[74:75], v15 offset0:214 offset1:247
	ds_read2_b32 v[76:77], v15 offset0:24 offset1:57
	ds_read2_b32 v[78:79], v15 offset0:90 offset1:123
	ds_read2_b32 v[80:81], v15 offset0:156 offset1:189
	ds_read2_b32 v[82:83], v15 offset0:222 offset1:255
	s_add_u32 s95, s94, 0xc00
	s_lshr_b32 vcc_lo, s95, 7
	s_and_b32 vcc_hi, s95, 0x7f
	s_mul_i32 vcc_hi, vcc_hi, 0xac000
	s_lshl_b32 vcc_lo, vcc_lo, 7
	s_add_u32 s98, s66, 0x12d00000
	s_addc_u32 s99, s67, 0
	s_add_u32 s98, s98, vcc_hi
	s_addc_u32 s99, s99, 0
	s_add_u32 s98, s98, vcc_lo
	s_addc_u32 s99, s99, 0
	s_waitcnt lgkmcnt(0)
	v_cvt_pk_bf16_f32 v84, v52, v53
	v_cvt_pk_bf16_f32 v85, v54, v55
	v_cvt_pk_bf16_f32 v86, v56, v57
	v_cvt_pk_bf16_f32 v87, v58, v59
	v_cvt_pk_bf16_f32 v88, v60, v61
	v_cvt_pk_bf16_f32 v89, v62, v63
	v_cvt_pk_bf16_f32 v90, v64, v65
	v_cvt_pk_bf16_f32 v91, v66, v67
	v_cvt_pk_bf16_f32 v92, v68, v69
	v_cvt_pk_bf16_f32 v93, v70, v71
	v_cvt_pk_bf16_f32 v94, v72, v73
	v_cvt_pk_bf16_f32 v95, v74, v75
	v_cvt_pk_bf16_f32 v96, v76, v77
	v_cvt_pk_bf16_f32 v97, v78, v79
	v_cvt_pk_bf16_f32 v98, v80, v81
	v_cvt_pk_bf16_f32 v99, v82, v83
	global_store_dwordx4 v16, v[84:87], s[98:99]
	global_store_dwordx4 v17, v[88:91], s[98:99]
	global_store_dwordx4 v18, v[92:95], s[98:99]
	global_store_dwordx4 v19, v[96:99], s[98:99]
	s_waitcnt vmcnt(23)
	ds_write_b32 v14, v20 offset:0
	ds_write_b32 v14, v21 offset:4
	ds_write_b32 v14, v22 offset:8
	ds_write_b32 v14, v23 offset:12
	s_waitcnt vmcnt(22)
	ds_write_b32 v14, v24 offset:1056
	ds_write_b32 v14, v25 offset:1060
	ds_write_b32 v14, v26 offset:1064
	ds_write_b32 v14, v27 offset:1068
	s_waitcnt vmcnt(21)
	ds_write_b32 v14, v28 offset:2112
	ds_write_b32 v14, v29 offset:2116
	ds_write_b32 v14, v30 offset:2120
	ds_write_b32 v14, v31 offset:2124
	s_waitcnt vmcnt(20)
	ds_write_b32 v14, v32 offset:3168
	ds_write_b32 v14, v33 offset:3172
	ds_write_b32 v14, v34 offset:3176
	ds_write_b32 v14, v35 offset:3180
	s_waitcnt vmcnt(19)
	ds_write_b32 v14, v36 offset:4224
	ds_write_b32 v14, v37 offset:4228
	ds_write_b32 v14, v38 offset:4232
	ds_write_b32 v14, v39 offset:4236
	s_waitcnt vmcnt(18)
	ds_write_b32 v14, v40 offset:5280
	ds_write_b32 v14, v41 offset:5284
	ds_write_b32 v14, v42 offset:5288
	ds_write_b32 v14, v43 offset:5292
	s_waitcnt vmcnt(17)
	ds_write_b32 v14, v44 offset:6336
	ds_write_b32 v14, v45 offset:6340
	ds_write_b32 v14, v46 offset:6344
	ds_write_b32 v14, v47 offset:6348
	s_waitcnt vmcnt(16)
	ds_write_b32 v14, v48 offset:7392
	ds_write_b32 v14, v49 offset:7396
	ds_write_b32 v14, v50 offset:7400
	ds_write_b32 v14, v51 offset:7404
	s_add_u32 s95, s94, 0x1800
	s_lshr_b32 vcc_lo, s95, 7
	s_and_b32 vcc_hi, s95, 0x7f
	s_lshl_b32 vcc_lo, vcc_lo, 20
	s_lshl_b32 vcc_hi, vcc_hi, 7
	s_add_u32 s96, s100, vcc_lo
	s_addc_u32 s97, s101, 0
	s_add_u32 s96, s96, vcc_hi
	s_addc_u32 s97, s97, 0
	global_load_dwordx4 v[20:23], v6, s[96:97]
	global_load_dwordx4 v[24:27], v7, s[96:97]
	global_load_dwordx4 v[28:31], v8, s[96:97]
	global_load_dwordx4 v[32:35], v9, s[96:97]
	global_load_dwordx4 v[36:39], v10, s[96:97]
	global_load_dwordx4 v[40:43], v11, s[96:97]
	global_load_dwordx4 v[44:47], v12, s[96:97]
	global_load_dwordx4 v[48:51], v13, s[96:97]
	ds_read2_b32 v[52:53], v15 offset0:0 offset1:33
	ds_read2_b32 v[54:55], v15 offset0:66 offset1:99
	ds_read2_b32 v[56:57], v15 offset0:132 offset1:165
	ds_read2_b32 v[58:59], v15 offset0:198 offset1:231
	ds_read2_b32 v[60:61], v15 offset0:8 offset1:41
	ds_read2_b32 v[62:63], v15 offset0:74 offset1:107
	ds_read2_b32 v[64:65], v15 offset0:140 offset1:173
	ds_read2_b32 v[66:67], v15 offset0:206 offset1:239
	ds_read2_b32 v[68:69], v15 offset0:16 offset1:49
	ds_read2_b32 v[70:71], v15 offset0:82 offset1:115
	ds_read2_b32 v[72:73], v15 offset0:148 offset1:181
	ds_read2_b32 v[74:75], v15 offset0:214 offset1:247
	ds_read2_b32 v[76:77], v15 offset0:24 offset1:57
	ds_read2_b32 v[78:79], v15 offset0:90 offset1:123
	ds_read2_b32 v[80:81], v15 offset0:156 offset1:189
	ds_read2_b32 v[82:83], v15 offset0:222 offset1:255
	s_add_u32 s95, s94, 0x1000
	s_lshr_b32 vcc_lo, s95, 7
	s_and_b32 vcc_hi, s95, 0x7f
	s_mul_i32 vcc_hi, vcc_hi, 0xac000
	s_lshl_b32 vcc_lo, vcc_lo, 7
	s_add_u32 s98, s66, 0x12d00000
	s_addc_u32 s99, s67, 0
	s_add_u32 s98, s98, vcc_hi
	s_addc_u32 s99, s99, 0
	s_add_u32 s98, s98, vcc_lo
	s_addc_u32 s99, s99, 0
	s_waitcnt lgkmcnt(0)
	v_cvt_pk_bf16_f32 v84, v52, v53
	v_cvt_pk_bf16_f32 v85, v54, v55
	v_cvt_pk_bf16_f32 v86, v56, v57
	v_cvt_pk_bf16_f32 v87, v58, v59
	v_cvt_pk_bf16_f32 v88, v60, v61
	v_cvt_pk_bf16_f32 v89, v62, v63
	v_cvt_pk_bf16_f32 v90, v64, v65
	v_cvt_pk_bf16_f32 v91, v66, v67
	v_cvt_pk_bf16_f32 v92, v68, v69
	v_cvt_pk_bf16_f32 v93, v70, v71
	v_cvt_pk_bf16_f32 v94, v72, v73
	v_cvt_pk_bf16_f32 v95, v74, v75
	v_cvt_pk_bf16_f32 v96, v76, v77
	v_cvt_pk_bf16_f32 v97, v78, v79
	v_cvt_pk_bf16_f32 v98, v80, v81
	v_cvt_pk_bf16_f32 v99, v82, v83
	global_store_dwordx4 v16, v[84:87], s[98:99]
	global_store_dwordx4 v17, v[88:91], s[98:99]
	global_store_dwordx4 v18, v[92:95], s[98:99]
	global_store_dwordx4 v19, v[96:99], s[98:99]
	s_waitcnt vmcnt(23)
	ds_write_b32 v14, v100 offset:0
	ds_write_b32 v14, v101 offset:4
	ds_write_b32 v14, v102 offset:8
	ds_write_b32 v14, v103 offset:12
	s_waitcnt vmcnt(22)
	ds_write_b32 v14, v104 offset:1056
	ds_write_b32 v14, v105 offset:1060
	ds_write_b32 v14, v106 offset:1064
	ds_write_b32 v14, v107 offset:1068
	s_waitcnt vmcnt(21)
	ds_write_b32 v14, v108 offset:2112
	ds_write_b32 v14, v109 offset:2116
	ds_write_b32 v14, v110 offset:2120
	ds_write_b32 v14, v111 offset:2124
	s_waitcnt vmcnt(20)
	ds_write_b32 v14, v112 offset:3168
	ds_write_b32 v14, v113 offset:3172
	ds_write_b32 v14, v114 offset:3176
	ds_write_b32 v14, v115 offset:3180
	s_waitcnt vmcnt(19)
	ds_write_b32 v14, v116 offset:4224
	ds_write_b32 v14, v117 offset:4228
	ds_write_b32 v14, v118 offset:4232
	ds_write_b32 v14, v119 offset:4236
	s_waitcnt vmcnt(18)
	ds_write_b32 v14, v120 offset:5280
	ds_write_b32 v14, v121 offset:5284
	ds_write_b32 v14, v122 offset:5288
	ds_write_b32 v14, v123 offset:5292
	s_waitcnt vmcnt(17)
	ds_write_b32 v14, v124 offset:6336
	ds_write_b32 v14, v125 offset:6340
	ds_write_b32 v14, v126 offset:6344
	ds_write_b32 v14, v127 offset:6348
	s_waitcnt vmcnt(16)
	ds_write_b32 v14, v128 offset:7392
	ds_write_b32 v14, v129 offset:7396
	ds_write_b32 v14, v130 offset:7400
	ds_write_b32 v14, v131 offset:7404
	s_add_u32 s95, s94, 0x1c00
	s_lshr_b32 vcc_lo, s95, 7
	s_and_b32 vcc_hi, s95, 0x7f
	s_lshl_b32 vcc_lo, vcc_lo, 20
	s_lshl_b32 vcc_hi, vcc_hi, 7
	s_add_u32 s96, s100, vcc_lo
	s_addc_u32 s97, s101, 0
	s_add_u32 s96, s96, vcc_hi
	s_addc_u32 s97, s97, 0
	global_load_dwordx4 v[100:103], v6, s[96:97]
	global_load_dwordx4 v[104:107], v7, s[96:97]
	global_load_dwordx4 v[108:111], v8, s[96:97]
	global_load_dwordx4 v[112:115], v9, s[96:97]
	global_load_dwordx4 v[116:119], v10, s[96:97]
	global_load_dwordx4 v[120:123], v11, s[96:97]
	global_load_dwordx4 v[124:127], v12, s[96:97]
	global_load_dwordx4 v[128:131], v13, s[96:97]
	ds_read2_b32 v[52:53], v15 offset0:0 offset1:33
	ds_read2_b32 v[54:55], v15 offset0:66 offset1:99
	ds_read2_b32 v[56:57], v15 offset0:132 offset1:165
	ds_read2_b32 v[58:59], v15 offset0:198 offset1:231
	ds_read2_b32 v[60:61], v15 offset0:8 offset1:41
	ds_read2_b32 v[62:63], v15 offset0:74 offset1:107
	ds_read2_b32 v[64:65], v15 offset0:140 offset1:173
	ds_read2_b32 v[66:67], v15 offset0:206 offset1:239
	ds_read2_b32 v[68:69], v15 offset0:16 offset1:49
	ds_read2_b32 v[70:71], v15 offset0:82 offset1:115
	ds_read2_b32 v[72:73], v15 offset0:148 offset1:181
	ds_read2_b32 v[74:75], v15 offset0:214 offset1:247
	ds_read2_b32 v[76:77], v15 offset0:24 offset1:57
	ds_read2_b32 v[78:79], v15 offset0:90 offset1:123
	ds_read2_b32 v[80:81], v15 offset0:156 offset1:189
	ds_read2_b32 v[82:83], v15 offset0:222 offset1:255
	s_add_u32 s95, s94, 0x1400
	s_lshr_b32 vcc_lo, s95, 7
	s_and_b32 vcc_hi, s95, 0x7f
	s_mul_i32 vcc_hi, vcc_hi, 0xac000
	s_lshl_b32 vcc_lo, vcc_lo, 7
	s_add_u32 s98, s66, 0x12d00000
	s_addc_u32 s99, s67, 0
	s_add_u32 s98, s98, vcc_hi
	s_addc_u32 s99, s99, 0
	s_add_u32 s98, s98, vcc_lo
	s_addc_u32 s99, s99, 0
	s_waitcnt lgkmcnt(0)
	v_cvt_pk_bf16_f32 v84, v52, v53
	v_cvt_pk_bf16_f32 v85, v54, v55
	v_cvt_pk_bf16_f32 v86, v56, v57
	v_cvt_pk_bf16_f32 v87, v58, v59
	v_cvt_pk_bf16_f32 v88, v60, v61
	v_cvt_pk_bf16_f32 v89, v62, v63
	v_cvt_pk_bf16_f32 v90, v64, v65
	v_cvt_pk_bf16_f32 v91, v66, v67
	v_cvt_pk_bf16_f32 v92, v68, v69
	v_cvt_pk_bf16_f32 v93, v70, v71
	v_cvt_pk_bf16_f32 v94, v72, v73
	v_cvt_pk_bf16_f32 v95, v74, v75
	v_cvt_pk_bf16_f32 v96, v76, v77
	v_cvt_pk_bf16_f32 v97, v78, v79
	v_cvt_pk_bf16_f32 v98, v80, v81
	v_cvt_pk_bf16_f32 v99, v82, v83
	global_store_dwordx4 v16, v[84:87], s[98:99]
	global_store_dwordx4 v17, v[88:91], s[98:99]
	global_store_dwordx4 v18, v[92:95], s[98:99]
	global_store_dwordx4 v19, v[96:99], s[98:99]
	s_waitcnt vmcnt(23)
	ds_write_b32 v14, v20 offset:0
	ds_write_b32 v14, v21 offset:4
	ds_write_b32 v14, v22 offset:8
	ds_write_b32 v14, v23 offset:12
	s_waitcnt vmcnt(22)
	ds_write_b32 v14, v24 offset:1056
	ds_write_b32 v14, v25 offset:1060
	ds_write_b32 v14, v26 offset:1064
	ds_write_b32 v14, v27 offset:1068
	s_waitcnt vmcnt(21)
	ds_write_b32 v14, v28 offset:2112
	ds_write_b32 v14, v29 offset:2116
	ds_write_b32 v14, v30 offset:2120
	ds_write_b32 v14, v31 offset:2124
	s_waitcnt vmcnt(20)
	ds_write_b32 v14, v32 offset:3168
	ds_write_b32 v14, v33 offset:3172
	ds_write_b32 v14, v34 offset:3176
	ds_write_b32 v14, v35 offset:3180
	s_waitcnt vmcnt(19)
	ds_write_b32 v14, v36 offset:4224
	ds_write_b32 v14, v37 offset:4228
	ds_write_b32 v14, v38 offset:4232
	ds_write_b32 v14, v39 offset:4236
	s_waitcnt vmcnt(18)
	ds_write_b32 v14, v40 offset:5280
	ds_write_b32 v14, v41 offset:5284
	ds_write_b32 v14, v42 offset:5288
	ds_write_b32 v14, v43 offset:5292
	s_waitcnt vmcnt(17)
	ds_write_b32 v14, v44 offset:6336
	ds_write_b32 v14, v45 offset:6340
	ds_write_b32 v14, v46 offset:6344
	ds_write_b32 v14, v47 offset:6348
	s_waitcnt vmcnt(16)
	ds_write_b32 v14, v48 offset:7392
	ds_write_b32 v14, v49 offset:7396
	ds_write_b32 v14, v50 offset:7400
	ds_write_b32 v14, v51 offset:7404
	s_add_u32 s95, s94, 0x2000
	s_lshr_b32 vcc_lo, s95, 7
	s_and_b32 vcc_hi, s95, 0x7f
	s_lshl_b32 vcc_lo, vcc_lo, 20
	s_lshl_b32 vcc_hi, vcc_hi, 7
	s_add_u32 s96, s100, vcc_lo
	s_addc_u32 s97, s101, 0
	s_add_u32 s96, s96, vcc_hi
	s_addc_u32 s97, s97, 0
	global_load_dwordx4 v[20:23], v6, s[96:97]
	global_load_dwordx4 v[24:27], v7, s[96:97]
	global_load_dwordx4 v[28:31], v8, s[96:97]
	global_load_dwordx4 v[32:35], v9, s[96:97]
	global_load_dwordx4 v[36:39], v10, s[96:97]
	global_load_dwordx4 v[40:43], v11, s[96:97]
	global_load_dwordx4 v[44:47], v12, s[96:97]
	global_load_dwordx4 v[48:51], v13, s[96:97]
	ds_read2_b32 v[52:53], v15 offset0:0 offset1:33
	ds_read2_b32 v[54:55], v15 offset0:66 offset1:99
	ds_read2_b32 v[56:57], v15 offset0:132 offset1:165
	ds_read2_b32 v[58:59], v15 offset0:198 offset1:231
	ds_read2_b32 v[60:61], v15 offset0:8 offset1:41
	ds_read2_b32 v[62:63], v15 offset0:74 offset1:107
	ds_read2_b32 v[64:65], v15 offset0:140 offset1:173
	ds_read2_b32 v[66:67], v15 offset0:206 offset1:239
	ds_read2_b32 v[68:69], v15 offset0:16 offset1:49
	ds_read2_b32 v[70:71], v15 offset0:82 offset1:115
	ds_read2_b32 v[72:73], v15 offset0:148 offset1:181
	ds_read2_b32 v[74:75], v15 offset0:214 offset1:247
	ds_read2_b32 v[76:77], v15 offset0:24 offset1:57
	ds_read2_b32 v[78:79], v15 offset0:90 offset1:123
	ds_read2_b32 v[80:81], v15 offset0:156 offset1:189
	ds_read2_b32 v[82:83], v15 offset0:222 offset1:255
	s_add_u32 s95, s94, 0x1800
	s_lshr_b32 vcc_lo, s95, 7
	s_and_b32 vcc_hi, s95, 0x7f
	s_mul_i32 vcc_hi, vcc_hi, 0xac000
	s_lshl_b32 vcc_lo, vcc_lo, 7
	s_add_u32 s98, s66, 0x12d00000
	s_addc_u32 s99, s67, 0
	s_add_u32 s98, s98, vcc_hi
	s_addc_u32 s99, s99, 0
	s_add_u32 s98, s98, vcc_lo
	s_addc_u32 s99, s99, 0
	s_waitcnt lgkmcnt(0)
	v_cvt_pk_bf16_f32 v84, v52, v53
	v_cvt_pk_bf16_f32 v85, v54, v55
	v_cvt_pk_bf16_f32 v86, v56, v57
	v_cvt_pk_bf16_f32 v87, v58, v59
	v_cvt_pk_bf16_f32 v88, v60, v61
	v_cvt_pk_bf16_f32 v89, v62, v63
	v_cvt_pk_bf16_f32 v90, v64, v65
	v_cvt_pk_bf16_f32 v91, v66, v67
	v_cvt_pk_bf16_f32 v92, v68, v69
	v_cvt_pk_bf16_f32 v93, v70, v71
	v_cvt_pk_bf16_f32 v94, v72, v73
	v_cvt_pk_bf16_f32 v95, v74, v75
	v_cvt_pk_bf16_f32 v96, v76, v77
	v_cvt_pk_bf16_f32 v97, v78, v79
	v_cvt_pk_bf16_f32 v98, v80, v81
	v_cvt_pk_bf16_f32 v99, v82, v83
	global_store_dwordx4 v16, v[84:87], s[98:99]
	global_store_dwordx4 v17, v[88:91], s[98:99]
	global_store_dwordx4 v18, v[92:95], s[98:99]
	global_store_dwordx4 v19, v[96:99], s[98:99]
	s_waitcnt vmcnt(23)
	ds_write_b32 v14, v100 offset:0
	ds_write_b32 v14, v101 offset:4
	ds_write_b32 v14, v102 offset:8
	ds_write_b32 v14, v103 offset:12
	s_waitcnt vmcnt(22)
	ds_write_b32 v14, v104 offset:1056
	ds_write_b32 v14, v105 offset:1060
	ds_write_b32 v14, v106 offset:1064
	ds_write_b32 v14, v107 offset:1068
	s_waitcnt vmcnt(21)
	ds_write_b32 v14, v108 offset:2112
	ds_write_b32 v14, v109 offset:2116
	ds_write_b32 v14, v110 offset:2120
	ds_write_b32 v14, v111 offset:2124
	s_waitcnt vmcnt(20)
	ds_write_b32 v14, v112 offset:3168
	ds_write_b32 v14, v113 offset:3172
	ds_write_b32 v14, v114 offset:3176
	ds_write_b32 v14, v115 offset:3180
	s_waitcnt vmcnt(19)
	ds_write_b32 v14, v116 offset:4224
	ds_write_b32 v14, v117 offset:4228
	ds_write_b32 v14, v118 offset:4232
	ds_write_b32 v14, v119 offset:4236
	s_waitcnt vmcnt(18)
	ds_write_b32 v14, v120 offset:5280
	ds_write_b32 v14, v121 offset:5284
	ds_write_b32 v14, v122 offset:5288
	ds_write_b32 v14, v123 offset:5292
	s_waitcnt vmcnt(17)
	ds_write_b32 v14, v124 offset:6336
	ds_write_b32 v14, v125 offset:6340
	ds_write_b32 v14, v126 offset:6344
	ds_write_b32 v14, v127 offset:6348
	s_waitcnt vmcnt(16)
	ds_write_b32 v14, v128 offset:7392
	ds_write_b32 v14, v129 offset:7396
	ds_write_b32 v14, v130 offset:7400
	ds_write_b32 v14, v131 offset:7404
	s_add_u32 s95, s94, 0x2400
	s_lshr_b32 vcc_lo, s95, 7
	s_and_b32 vcc_hi, s95, 0x7f
	s_lshl_b32 vcc_lo, vcc_lo, 20
	s_lshl_b32 vcc_hi, vcc_hi, 7
	s_add_u32 s96, s100, vcc_lo
	s_addc_u32 s97, s101, 0
	s_add_u32 s96, s96, vcc_hi
	s_addc_u32 s97, s97, 0
	global_load_dwordx4 v[100:103], v6, s[96:97]
	global_load_dwordx4 v[104:107], v7, s[96:97]
	global_load_dwordx4 v[108:111], v8, s[96:97]
	global_load_dwordx4 v[112:115], v9, s[96:97]
	global_load_dwordx4 v[116:119], v10, s[96:97]
	global_load_dwordx4 v[120:123], v11, s[96:97]
	global_load_dwordx4 v[124:127], v12, s[96:97]
	global_load_dwordx4 v[128:131], v13, s[96:97]
	ds_read2_b32 v[52:53], v15 offset0:0 offset1:33
	ds_read2_b32 v[54:55], v15 offset0:66 offset1:99
	ds_read2_b32 v[56:57], v15 offset0:132 offset1:165
	ds_read2_b32 v[58:59], v15 offset0:198 offset1:231
	ds_read2_b32 v[60:61], v15 offset0:8 offset1:41
	ds_read2_b32 v[62:63], v15 offset0:74 offset1:107
	ds_read2_b32 v[64:65], v15 offset0:140 offset1:173
	ds_read2_b32 v[66:67], v15 offset0:206 offset1:239
	ds_read2_b32 v[68:69], v15 offset0:16 offset1:49
	ds_read2_b32 v[70:71], v15 offset0:82 offset1:115
	ds_read2_b32 v[72:73], v15 offset0:148 offset1:181
	ds_read2_b32 v[74:75], v15 offset0:214 offset1:247
	ds_read2_b32 v[76:77], v15 offset0:24 offset1:57
	ds_read2_b32 v[78:79], v15 offset0:90 offset1:123
	ds_read2_b32 v[80:81], v15 offset0:156 offset1:189
	ds_read2_b32 v[82:83], v15 offset0:222 offset1:255
	s_add_u32 s95, s94, 0x1c00
	s_lshr_b32 vcc_lo, s95, 7
	s_and_b32 vcc_hi, s95, 0x7f
	s_mul_i32 vcc_hi, vcc_hi, 0xac000
	s_lshl_b32 vcc_lo, vcc_lo, 7
	s_add_u32 s98, s66, 0x12d00000
	s_addc_u32 s99, s67, 0
	s_add_u32 s98, s98, vcc_hi
	s_addc_u32 s99, s99, 0
	s_add_u32 s98, s98, vcc_lo
	s_addc_u32 s99, s99, 0
	s_waitcnt lgkmcnt(0)
	v_cvt_pk_bf16_f32 v84, v52, v53
	v_cvt_pk_bf16_f32 v85, v54, v55
	v_cvt_pk_bf16_f32 v86, v56, v57
	v_cvt_pk_bf16_f32 v87, v58, v59
	v_cvt_pk_bf16_f32 v88, v60, v61
	v_cvt_pk_bf16_f32 v89, v62, v63
	v_cvt_pk_bf16_f32 v90, v64, v65
	v_cvt_pk_bf16_f32 v91, v66, v67
	v_cvt_pk_bf16_f32 v92, v68, v69
	v_cvt_pk_bf16_f32 v93, v70, v71
	v_cvt_pk_bf16_f32 v94, v72, v73
	v_cvt_pk_bf16_f32 v95, v74, v75
	v_cvt_pk_bf16_f32 v96, v76, v77
	v_cvt_pk_bf16_f32 v97, v78, v79
	v_cvt_pk_bf16_f32 v98, v80, v81
	v_cvt_pk_bf16_f32 v99, v82, v83
	global_store_dwordx4 v16, v[84:87], s[98:99]
	global_store_dwordx4 v17, v[88:91], s[98:99]
	global_store_dwordx4 v18, v[92:95], s[98:99]
	global_store_dwordx4 v19, v[96:99], s[98:99]
	s_waitcnt vmcnt(23)
	ds_write_b32 v14, v20 offset:0
	ds_write_b32 v14, v21 offset:4
	ds_write_b32 v14, v22 offset:8
	ds_write_b32 v14, v23 offset:12
	s_waitcnt vmcnt(22)
	ds_write_b32 v14, v24 offset:1056
	ds_write_b32 v14, v25 offset:1060
	ds_write_b32 v14, v26 offset:1064
	ds_write_b32 v14, v27 offset:1068
	s_waitcnt vmcnt(21)
	ds_write_b32 v14, v28 offset:2112
	ds_write_b32 v14, v29 offset:2116
	ds_write_b32 v14, v30 offset:2120
	ds_write_b32 v14, v31 offset:2124
	s_waitcnt vmcnt(20)
	ds_write_b32 v14, v32 offset:3168
	ds_write_b32 v14, v33 offset:3172
	ds_write_b32 v14, v34 offset:3176
	ds_write_b32 v14, v35 offset:3180
	s_waitcnt vmcnt(19)
	ds_write_b32 v14, v36 offset:4224
	ds_write_b32 v14, v37 offset:4228
	ds_write_b32 v14, v38 offset:4232
	ds_write_b32 v14, v39 offset:4236
	s_waitcnt vmcnt(18)
	ds_write_b32 v14, v40 offset:5280
	ds_write_b32 v14, v41 offset:5284
	ds_write_b32 v14, v42 offset:5288
	ds_write_b32 v14, v43 offset:5292
	s_waitcnt vmcnt(17)
	ds_write_b32 v14, v44 offset:6336
	ds_write_b32 v14, v45 offset:6340
	ds_write_b32 v14, v46 offset:6344
	ds_write_b32 v14, v47 offset:6348
	s_waitcnt vmcnt(16)
	ds_write_b32 v14, v48 offset:7392
	ds_write_b32 v14, v49 offset:7396
	ds_write_b32 v14, v50 offset:7400
	ds_write_b32 v14, v51 offset:7404
	s_add_u32 s95, s94, 0x2800
	s_lshr_b32 vcc_lo, s95, 7
	s_and_b32 vcc_hi, s95, 0x7f
	s_lshl_b32 vcc_lo, vcc_lo, 20
	s_lshl_b32 vcc_hi, vcc_hi, 7
	s_add_u32 s96, s100, vcc_lo
	s_addc_u32 s97, s101, 0
	s_add_u32 s96, s96, vcc_hi
	s_addc_u32 s97, s97, 0
	global_load_dwordx4 v[20:23], v6, s[96:97]
	global_load_dwordx4 v[24:27], v7, s[96:97]
	global_load_dwordx4 v[28:31], v8, s[96:97]
	global_load_dwordx4 v[32:35], v9, s[96:97]
	global_load_dwordx4 v[36:39], v10, s[96:97]
	global_load_dwordx4 v[40:43], v11, s[96:97]
	global_load_dwordx4 v[44:47], v12, s[96:97]
	global_load_dwordx4 v[48:51], v13, s[96:97]
	ds_read2_b32 v[52:53], v15 offset0:0 offset1:33
	ds_read2_b32 v[54:55], v15 offset0:66 offset1:99
	ds_read2_b32 v[56:57], v15 offset0:132 offset1:165
	ds_read2_b32 v[58:59], v15 offset0:198 offset1:231
	ds_read2_b32 v[60:61], v15 offset0:8 offset1:41
	ds_read2_b32 v[62:63], v15 offset0:74 offset1:107
	ds_read2_b32 v[64:65], v15 offset0:140 offset1:173
	ds_read2_b32 v[66:67], v15 offset0:206 offset1:239
	ds_read2_b32 v[68:69], v15 offset0:16 offset1:49
	ds_read2_b32 v[70:71], v15 offset0:82 offset1:115
	ds_read2_b32 v[72:73], v15 offset0:148 offset1:181
	ds_read2_b32 v[74:75], v15 offset0:214 offset1:247
	ds_read2_b32 v[76:77], v15 offset0:24 offset1:57
	ds_read2_b32 v[78:79], v15 offset0:90 offset1:123
	ds_read2_b32 v[80:81], v15 offset0:156 offset1:189
	ds_read2_b32 v[82:83], v15 offset0:222 offset1:255
	s_add_u32 s95, s94, 0x2000
	s_lshr_b32 vcc_lo, s95, 7
	s_and_b32 vcc_hi, s95, 0x7f
	s_mul_i32 vcc_hi, vcc_hi, 0xac000
	s_lshl_b32 vcc_lo, vcc_lo, 7
	s_add_u32 s98, s66, 0x12d00000
	s_addc_u32 s99, s67, 0
	s_add_u32 s98, s98, vcc_hi
	s_addc_u32 s99, s99, 0
	s_add_u32 s98, s98, vcc_lo
	s_addc_u32 s99, s99, 0
	s_waitcnt lgkmcnt(0)
	v_cvt_pk_bf16_f32 v84, v52, v53
	v_cvt_pk_bf16_f32 v85, v54, v55
	v_cvt_pk_bf16_f32 v86, v56, v57
	v_cvt_pk_bf16_f32 v87, v58, v59
	v_cvt_pk_bf16_f32 v88, v60, v61
	v_cvt_pk_bf16_f32 v89, v62, v63
	v_cvt_pk_bf16_f32 v90, v64, v65
	v_cvt_pk_bf16_f32 v91, v66, v67
	v_cvt_pk_bf16_f32 v92, v68, v69
	v_cvt_pk_bf16_f32 v93, v70, v71
	v_cvt_pk_bf16_f32 v94, v72, v73
	v_cvt_pk_bf16_f32 v95, v74, v75
	v_cvt_pk_bf16_f32 v96, v76, v77
	v_cvt_pk_bf16_f32 v97, v78, v79
	v_cvt_pk_bf16_f32 v98, v80, v81
	v_cvt_pk_bf16_f32 v99, v82, v83
	global_store_dwordx4 v16, v[84:87], s[98:99]
	global_store_dwordx4 v17, v[88:91], s[98:99]
	global_store_dwordx4 v18, v[92:95], s[98:99]
	global_store_dwordx4 v19, v[96:99], s[98:99]
	s_waitcnt vmcnt(23)
	ds_write_b32 v14, v100 offset:0
	ds_write_b32 v14, v101 offset:4
	ds_write_b32 v14, v102 offset:8
	ds_write_b32 v14, v103 offset:12
	s_waitcnt vmcnt(22)
	ds_write_b32 v14, v104 offset:1056
	ds_write_b32 v14, v105 offset:1060
	ds_write_b32 v14, v106 offset:1064
	ds_write_b32 v14, v107 offset:1068
	s_waitcnt vmcnt(21)
	ds_write_b32 v14, v108 offset:2112
	ds_write_b32 v14, v109 offset:2116
	ds_write_b32 v14, v110 offset:2120
	ds_write_b32 v14, v111 offset:2124
	s_waitcnt vmcnt(20)
	ds_write_b32 v14, v112 offset:3168
	ds_write_b32 v14, v113 offset:3172
	ds_write_b32 v14, v114 offset:3176
	ds_write_b32 v14, v115 offset:3180
	s_waitcnt vmcnt(19)
	ds_write_b32 v14, v116 offset:4224
	ds_write_b32 v14, v117 offset:4228
	ds_write_b32 v14, v118 offset:4232
	ds_write_b32 v14, v119 offset:4236
	s_waitcnt vmcnt(18)
	ds_write_b32 v14, v120 offset:5280
	ds_write_b32 v14, v121 offset:5284
	ds_write_b32 v14, v122 offset:5288
	ds_write_b32 v14, v123 offset:5292
	s_waitcnt vmcnt(17)
	ds_write_b32 v14, v124 offset:6336
	ds_write_b32 v14, v125 offset:6340
	ds_write_b32 v14, v126 offset:6344
	ds_write_b32 v14, v127 offset:6348
	s_waitcnt vmcnt(16)
	ds_write_b32 v14, v128 offset:7392
	ds_write_b32 v14, v129 offset:7396
	ds_write_b32 v14, v130 offset:7400
	ds_write_b32 v14, v131 offset:7404
	s_add_u32 s95, s94, 0x2c00
	s_lshr_b32 vcc_lo, s95, 7
	s_and_b32 vcc_hi, s95, 0x7f
	s_lshl_b32 vcc_lo, vcc_lo, 20
	s_lshl_b32 vcc_hi, vcc_hi, 7
	s_add_u32 s96, s100, vcc_lo
	s_addc_u32 s97, s101, 0
	s_add_u32 s96, s96, vcc_hi
	s_addc_u32 s97, s97, 0
	global_load_dwordx4 v[100:103], v6, s[96:97]
	global_load_dwordx4 v[104:107], v7, s[96:97]
	global_load_dwordx4 v[108:111], v8, s[96:97]
	global_load_dwordx4 v[112:115], v9, s[96:97]
	global_load_dwordx4 v[116:119], v10, s[96:97]
	global_load_dwordx4 v[120:123], v11, s[96:97]
	global_load_dwordx4 v[124:127], v12, s[96:97]
	global_load_dwordx4 v[128:131], v13, s[96:97]
	ds_read2_b32 v[52:53], v15 offset0:0 offset1:33
	ds_read2_b32 v[54:55], v15 offset0:66 offset1:99
	ds_read2_b32 v[56:57], v15 offset0:132 offset1:165
	ds_read2_b32 v[58:59], v15 offset0:198 offset1:231
	ds_read2_b32 v[60:61], v15 offset0:8 offset1:41
	ds_read2_b32 v[62:63], v15 offset0:74 offset1:107
	ds_read2_b32 v[64:65], v15 offset0:140 offset1:173
	ds_read2_b32 v[66:67], v15 offset0:206 offset1:239
	ds_read2_b32 v[68:69], v15 offset0:16 offset1:49
	ds_read2_b32 v[70:71], v15 offset0:82 offset1:115
	ds_read2_b32 v[72:73], v15 offset0:148 offset1:181
	ds_read2_b32 v[74:75], v15 offset0:214 offset1:247
	ds_read2_b32 v[76:77], v15 offset0:24 offset1:57
	ds_read2_b32 v[78:79], v15 offset0:90 offset1:123
	ds_read2_b32 v[80:81], v15 offset0:156 offset1:189
	ds_read2_b32 v[82:83], v15 offset0:222 offset1:255
	s_add_u32 s95, s94, 0x2400
	s_lshr_b32 vcc_lo, s95, 7
	s_and_b32 vcc_hi, s95, 0x7f
	s_mul_i32 vcc_hi, vcc_hi, 0xac000
	s_lshl_b32 vcc_lo, vcc_lo, 7
	s_add_u32 s98, s66, 0x12d00000
	s_addc_u32 s99, s67, 0
	s_add_u32 s98, s98, vcc_hi
	s_addc_u32 s99, s99, 0
	s_add_u32 s98, s98, vcc_lo
	s_addc_u32 s99, s99, 0
	s_waitcnt lgkmcnt(0)
	v_cvt_pk_bf16_f32 v84, v52, v53
	v_cvt_pk_bf16_f32 v85, v54, v55
	v_cvt_pk_bf16_f32 v86, v56, v57
	v_cvt_pk_bf16_f32 v87, v58, v59
	v_cvt_pk_bf16_f32 v88, v60, v61
	v_cvt_pk_bf16_f32 v89, v62, v63
	v_cvt_pk_bf16_f32 v90, v64, v65
	v_cvt_pk_bf16_f32 v91, v66, v67
	v_cvt_pk_bf16_f32 v92, v68, v69
	v_cvt_pk_bf16_f32 v93, v70, v71
	v_cvt_pk_bf16_f32 v94, v72, v73
	v_cvt_pk_bf16_f32 v95, v74, v75
	v_cvt_pk_bf16_f32 v96, v76, v77
	v_cvt_pk_bf16_f32 v97, v78, v79
	v_cvt_pk_bf16_f32 v98, v80, v81
	v_cvt_pk_bf16_f32 v99, v82, v83
	global_store_dwordx4 v16, v[84:87], s[98:99]
	global_store_dwordx4 v17, v[88:91], s[98:99]
	global_store_dwordx4 v18, v[92:95], s[98:99]
	global_store_dwordx4 v19, v[96:99], s[98:99]
	s_waitcnt vmcnt(23)
	ds_write_b32 v14, v20 offset:0
	ds_write_b32 v14, v21 offset:4
	ds_write_b32 v14, v22 offset:8
	ds_write_b32 v14, v23 offset:12
	s_waitcnt vmcnt(22)
	ds_write_b32 v14, v24 offset:1056
	ds_write_b32 v14, v25 offset:1060
	ds_write_b32 v14, v26 offset:1064
	ds_write_b32 v14, v27 offset:1068
	s_waitcnt vmcnt(21)
	ds_write_b32 v14, v28 offset:2112
	ds_write_b32 v14, v29 offset:2116
	ds_write_b32 v14, v30 offset:2120
	ds_write_b32 v14, v31 offset:2124
	s_waitcnt vmcnt(20)
	ds_write_b32 v14, v32 offset:3168
	ds_write_b32 v14, v33 offset:3172
	ds_write_b32 v14, v34 offset:3176
	ds_write_b32 v14, v35 offset:3180
	s_waitcnt vmcnt(19)
	ds_write_b32 v14, v36 offset:4224
	ds_write_b32 v14, v37 offset:4228
	ds_write_b32 v14, v38 offset:4232
	ds_write_b32 v14, v39 offset:4236
	s_waitcnt vmcnt(18)
	ds_write_b32 v14, v40 offset:5280
	ds_write_b32 v14, v41 offset:5284
	ds_write_b32 v14, v42 offset:5288
	ds_write_b32 v14, v43 offset:5292
	s_waitcnt vmcnt(17)
	ds_write_b32 v14, v44 offset:6336
	ds_write_b32 v14, v45 offset:6340
	ds_write_b32 v14, v46 offset:6344
	ds_write_b32 v14, v47 offset:6348
	s_waitcnt vmcnt(16)
	ds_write_b32 v14, v48 offset:7392
	ds_write_b32 v14, v49 offset:7396
	ds_write_b32 v14, v50 offset:7400
	ds_write_b32 v14, v51 offset:7404
	s_add_u32 s95, s94, 0x3000
	s_lshr_b32 vcc_lo, s95, 7
	s_and_b32 vcc_hi, s95, 0x7f
	s_lshl_b32 vcc_lo, vcc_lo, 20
	s_lshl_b32 vcc_hi, vcc_hi, 7
	s_add_u32 s96, s100, vcc_lo
	s_addc_u32 s97, s101, 0
	s_add_u32 s96, s96, vcc_hi
	s_addc_u32 s97, s97, 0
	global_load_dwordx4 v[20:23], v6, s[96:97]
	global_load_dwordx4 v[24:27], v7, s[96:97]
	global_load_dwordx4 v[28:31], v8, s[96:97]
	global_load_dwordx4 v[32:35], v9, s[96:97]
	global_load_dwordx4 v[36:39], v10, s[96:97]
	global_load_dwordx4 v[40:43], v11, s[96:97]
	global_load_dwordx4 v[44:47], v12, s[96:97]
	global_load_dwordx4 v[48:51], v13, s[96:97]
	ds_read2_b32 v[52:53], v15 offset0:0 offset1:33
	ds_read2_b32 v[54:55], v15 offset0:66 offset1:99
	ds_read2_b32 v[56:57], v15 offset0:132 offset1:165
	ds_read2_b32 v[58:59], v15 offset0:198 offset1:231
	ds_read2_b32 v[60:61], v15 offset0:8 offset1:41
	ds_read2_b32 v[62:63], v15 offset0:74 offset1:107
	ds_read2_b32 v[64:65], v15 offset0:140 offset1:173
	ds_read2_b32 v[66:67], v15 offset0:206 offset1:239
	ds_read2_b32 v[68:69], v15 offset0:16 offset1:49
	ds_read2_b32 v[70:71], v15 offset0:82 offset1:115
	ds_read2_b32 v[72:73], v15 offset0:148 offset1:181
	ds_read2_b32 v[74:75], v15 offset0:214 offset1:247
	ds_read2_b32 v[76:77], v15 offset0:24 offset1:57
	ds_read2_b32 v[78:79], v15 offset0:90 offset1:123
	ds_read2_b32 v[80:81], v15 offset0:156 offset1:189
	ds_read2_b32 v[82:83], v15 offset0:222 offset1:255
	s_add_u32 s95, s94, 0x2800
	s_lshr_b32 vcc_lo, s95, 7
	s_and_b32 vcc_hi, s95, 0x7f
	s_mul_i32 vcc_hi, vcc_hi, 0xac000
	s_lshl_b32 vcc_lo, vcc_lo, 7
	s_add_u32 s98, s66, 0x12d00000
	s_addc_u32 s99, s67, 0
	s_add_u32 s98, s98, vcc_hi
	s_addc_u32 s99, s99, 0
	s_add_u32 s98, s98, vcc_lo
	s_addc_u32 s99, s99, 0
	s_waitcnt lgkmcnt(0)
	v_cvt_pk_bf16_f32 v84, v52, v53
	v_cvt_pk_bf16_f32 v85, v54, v55
	v_cvt_pk_bf16_f32 v86, v56, v57
	v_cvt_pk_bf16_f32 v87, v58, v59
	v_cvt_pk_bf16_f32 v88, v60, v61
	v_cvt_pk_bf16_f32 v89, v62, v63
	v_cvt_pk_bf16_f32 v90, v64, v65
	v_cvt_pk_bf16_f32 v91, v66, v67
	v_cvt_pk_bf16_f32 v92, v68, v69
	v_cvt_pk_bf16_f32 v93, v70, v71
	v_cvt_pk_bf16_f32 v94, v72, v73
	v_cvt_pk_bf16_f32 v95, v74, v75
	v_cvt_pk_bf16_f32 v96, v76, v77
	v_cvt_pk_bf16_f32 v97, v78, v79
	v_cvt_pk_bf16_f32 v98, v80, v81
	v_cvt_pk_bf16_f32 v99, v82, v83
	global_store_dwordx4 v16, v[84:87], s[98:99]
	global_store_dwordx4 v17, v[88:91], s[98:99]
	global_store_dwordx4 v18, v[92:95], s[98:99]
	global_store_dwordx4 v19, v[96:99], s[98:99]
	s_waitcnt vmcnt(23)
	ds_write_b32 v14, v100 offset:0
	ds_write_b32 v14, v101 offset:4
	ds_write_b32 v14, v102 offset:8
	ds_write_b32 v14, v103 offset:12
	s_waitcnt vmcnt(22)
	ds_write_b32 v14, v104 offset:1056
	ds_write_b32 v14, v105 offset:1060
	ds_write_b32 v14, v106 offset:1064
	ds_write_b32 v14, v107 offset:1068
	s_waitcnt vmcnt(21)
	ds_write_b32 v14, v108 offset:2112
	ds_write_b32 v14, v109 offset:2116
	ds_write_b32 v14, v110 offset:2120
	ds_write_b32 v14, v111 offset:2124
	s_waitcnt vmcnt(20)
	ds_write_b32 v14, v112 offset:3168
	ds_write_b32 v14, v113 offset:3172
	ds_write_b32 v14, v114 offset:3176
	ds_write_b32 v14, v115 offset:3180
	s_waitcnt vmcnt(19)
	ds_write_b32 v14, v116 offset:4224
	ds_write_b32 v14, v117 offset:4228
	ds_write_b32 v14, v118 offset:4232
	ds_write_b32 v14, v119 offset:4236
	s_waitcnt vmcnt(18)
	ds_write_b32 v14, v120 offset:5280
	ds_write_b32 v14, v121 offset:5284
	ds_write_b32 v14, v122 offset:5288
	ds_write_b32 v14, v123 offset:5292
	s_waitcnt vmcnt(17)
	ds_write_b32 v14, v124 offset:6336
	ds_write_b32 v14, v125 offset:6340
	ds_write_b32 v14, v126 offset:6344
	ds_write_b32 v14, v127 offset:6348
	s_waitcnt vmcnt(16)
	ds_write_b32 v14, v128 offset:7392
	ds_write_b32 v14, v129 offset:7396
	ds_write_b32 v14, v130 offset:7400
	ds_write_b32 v14, v131 offset:7404
	s_add_u32 s95, s94, 0x3400
	s_lshr_b32 vcc_lo, s95, 7
	s_and_b32 vcc_hi, s95, 0x7f
	s_lshl_b32 vcc_lo, vcc_lo, 20
	s_lshl_b32 vcc_hi, vcc_hi, 7
	s_add_u32 s96, s100, vcc_lo
	s_addc_u32 s97, s101, 0
	s_add_u32 s96, s96, vcc_hi
	s_addc_u32 s97, s97, 0
	global_load_dwordx4 v[100:103], v6, s[96:97]
	global_load_dwordx4 v[104:107], v7, s[96:97]
	global_load_dwordx4 v[108:111], v8, s[96:97]
	global_load_dwordx4 v[112:115], v9, s[96:97]
	global_load_dwordx4 v[116:119], v10, s[96:97]
	global_load_dwordx4 v[120:123], v11, s[96:97]
	global_load_dwordx4 v[124:127], v12, s[96:97]
	global_load_dwordx4 v[128:131], v13, s[96:97]
	ds_read2_b32 v[52:53], v15 offset0:0 offset1:33
	ds_read2_b32 v[54:55], v15 offset0:66 offset1:99
	ds_read2_b32 v[56:57], v15 offset0:132 offset1:165
	ds_read2_b32 v[58:59], v15 offset0:198 offset1:231
	ds_read2_b32 v[60:61], v15 offset0:8 offset1:41
	ds_read2_b32 v[62:63], v15 offset0:74 offset1:107
	ds_read2_b32 v[64:65], v15 offset0:140 offset1:173
	ds_read2_b32 v[66:67], v15 offset0:206 offset1:239
	ds_read2_b32 v[68:69], v15 offset0:16 offset1:49
	ds_read2_b32 v[70:71], v15 offset0:82 offset1:115
	ds_read2_b32 v[72:73], v15 offset0:148 offset1:181
	ds_read2_b32 v[74:75], v15 offset0:214 offset1:247
	ds_read2_b32 v[76:77], v15 offset0:24 offset1:57
	ds_read2_b32 v[78:79], v15 offset0:90 offset1:123
	ds_read2_b32 v[80:81], v15 offset0:156 offset1:189
	ds_read2_b32 v[82:83], v15 offset0:222 offset1:255
	s_add_u32 s95, s94, 0x2c00
	s_lshr_b32 vcc_lo, s95, 7
	s_and_b32 vcc_hi, s95, 0x7f
	s_mul_i32 vcc_hi, vcc_hi, 0xac000
	s_lshl_b32 vcc_lo, vcc_lo, 7
	s_add_u32 s98, s66, 0x12d00000
	s_addc_u32 s99, s67, 0
	s_add_u32 s98, s98, vcc_hi
	s_addc_u32 s99, s99, 0
	s_add_u32 s98, s98, vcc_lo
	s_addc_u32 s99, s99, 0
	s_waitcnt lgkmcnt(0)
	v_cvt_pk_bf16_f32 v84, v52, v53
	v_cvt_pk_bf16_f32 v85, v54, v55
	v_cvt_pk_bf16_f32 v86, v56, v57
	v_cvt_pk_bf16_f32 v87, v58, v59
	v_cvt_pk_bf16_f32 v88, v60, v61
	v_cvt_pk_bf16_f32 v89, v62, v63
	v_cvt_pk_bf16_f32 v90, v64, v65
	v_cvt_pk_bf16_f32 v91, v66, v67
	v_cvt_pk_bf16_f32 v92, v68, v69
	v_cvt_pk_bf16_f32 v93, v70, v71
	v_cvt_pk_bf16_f32 v94, v72, v73
	v_cvt_pk_bf16_f32 v95, v74, v75
	v_cvt_pk_bf16_f32 v96, v76, v77
	v_cvt_pk_bf16_f32 v97, v78, v79
	v_cvt_pk_bf16_f32 v98, v80, v81
	v_cvt_pk_bf16_f32 v99, v82, v83
	global_store_dwordx4 v16, v[84:87], s[98:99]
	global_store_dwordx4 v17, v[88:91], s[98:99]
	global_store_dwordx4 v18, v[92:95], s[98:99]
	global_store_dwordx4 v19, v[96:99], s[98:99]
	s_waitcnt vmcnt(23)
	ds_write_b32 v14, v20 offset:0
	ds_write_b32 v14, v21 offset:4
	ds_write_b32 v14, v22 offset:8
	ds_write_b32 v14, v23 offset:12
	s_waitcnt vmcnt(22)
	ds_write_b32 v14, v24 offset:1056
	ds_write_b32 v14, v25 offset:1060
	ds_write_b32 v14, v26 offset:1064
	ds_write_b32 v14, v27 offset:1068
	s_waitcnt vmcnt(21)
	ds_write_b32 v14, v28 offset:2112
	ds_write_b32 v14, v29 offset:2116
	ds_write_b32 v14, v30 offset:2120
	ds_write_b32 v14, v31 offset:2124
	s_waitcnt vmcnt(20)
	ds_write_b32 v14, v32 offset:3168
	ds_write_b32 v14, v33 offset:3172
	ds_write_b32 v14, v34 offset:3176
	ds_write_b32 v14, v35 offset:3180
	s_waitcnt vmcnt(19)
	ds_write_b32 v14, v36 offset:4224
	ds_write_b32 v14, v37 offset:4228
	ds_write_b32 v14, v38 offset:4232
	ds_write_b32 v14, v39 offset:4236
	s_waitcnt vmcnt(18)
	ds_write_b32 v14, v40 offset:5280
	ds_write_b32 v14, v41 offset:5284
	ds_write_b32 v14, v42 offset:5288
	ds_write_b32 v14, v43 offset:5292
	s_waitcnt vmcnt(17)
	ds_write_b32 v14, v44 offset:6336
	ds_write_b32 v14, v45 offset:6340
	ds_write_b32 v14, v46 offset:6344
	ds_write_b32 v14, v47 offset:6348
	s_waitcnt vmcnt(16)
	ds_write_b32 v14, v48 offset:7392
	ds_write_b32 v14, v49 offset:7396
	ds_write_b32 v14, v50 offset:7400
	ds_write_b32 v14, v51 offset:7404
	s_add_u32 s95, s94, 0x3800
	s_lshr_b32 vcc_lo, s95, 7
	s_and_b32 vcc_hi, s95, 0x7f
	s_lshl_b32 vcc_lo, vcc_lo, 20
	s_lshl_b32 vcc_hi, vcc_hi, 7
	s_add_u32 s96, s100, vcc_lo
	s_addc_u32 s97, s101, 0
	s_add_u32 s96, s96, vcc_hi
	s_addc_u32 s97, s97, 0
	global_load_dwordx4 v[20:23], v6, s[96:97]
	global_load_dwordx4 v[24:27], v7, s[96:97]
	global_load_dwordx4 v[28:31], v8, s[96:97]
	global_load_dwordx4 v[32:35], v9, s[96:97]
	global_load_dwordx4 v[36:39], v10, s[96:97]
	global_load_dwordx4 v[40:43], v11, s[96:97]
	global_load_dwordx4 v[44:47], v12, s[96:97]
	global_load_dwordx4 v[48:51], v13, s[96:97]
	ds_read2_b32 v[52:53], v15 offset0:0 offset1:33
	ds_read2_b32 v[54:55], v15 offset0:66 offset1:99
	ds_read2_b32 v[56:57], v15 offset0:132 offset1:165
	ds_read2_b32 v[58:59], v15 offset0:198 offset1:231
	ds_read2_b32 v[60:61], v15 offset0:8 offset1:41
	ds_read2_b32 v[62:63], v15 offset0:74 offset1:107
	ds_read2_b32 v[64:65], v15 offset0:140 offset1:173
	ds_read2_b32 v[66:67], v15 offset0:206 offset1:239
	ds_read2_b32 v[68:69], v15 offset0:16 offset1:49
	ds_read2_b32 v[70:71], v15 offset0:82 offset1:115
	ds_read2_b32 v[72:73], v15 offset0:148 offset1:181
	ds_read2_b32 v[74:75], v15 offset0:214 offset1:247
	ds_read2_b32 v[76:77], v15 offset0:24 offset1:57
	ds_read2_b32 v[78:79], v15 offset0:90 offset1:123
	ds_read2_b32 v[80:81], v15 offset0:156 offset1:189
	ds_read2_b32 v[82:83], v15 offset0:222 offset1:255
	s_add_u32 s95, s94, 0x3000
	s_lshr_b32 vcc_lo, s95, 7
	s_and_b32 vcc_hi, s95, 0x7f
	s_mul_i32 vcc_hi, vcc_hi, 0xac000
	s_lshl_b32 vcc_lo, vcc_lo, 7
	s_add_u32 s98, s66, 0x12d00000
	s_addc_u32 s99, s67, 0
	s_add_u32 s98, s98, vcc_hi
	s_addc_u32 s99, s99, 0
	s_add_u32 s98, s98, vcc_lo
	s_addc_u32 s99, s99, 0
	s_waitcnt lgkmcnt(0)
	v_cvt_pk_bf16_f32 v84, v52, v53
	v_cvt_pk_bf16_f32 v85, v54, v55
	v_cvt_pk_bf16_f32 v86, v56, v57
	v_cvt_pk_bf16_f32 v87, v58, v59
	v_cvt_pk_bf16_f32 v88, v60, v61
	v_cvt_pk_bf16_f32 v89, v62, v63
	v_cvt_pk_bf16_f32 v90, v64, v65
	v_cvt_pk_bf16_f32 v91, v66, v67
	v_cvt_pk_bf16_f32 v92, v68, v69
	v_cvt_pk_bf16_f32 v93, v70, v71
	v_cvt_pk_bf16_f32 v94, v72, v73
	v_cvt_pk_bf16_f32 v95, v74, v75
	v_cvt_pk_bf16_f32 v96, v76, v77
	v_cvt_pk_bf16_f32 v97, v78, v79
	v_cvt_pk_bf16_f32 v98, v80, v81
	v_cvt_pk_bf16_f32 v99, v82, v83
	global_store_dwordx4 v16, v[84:87], s[98:99]
	global_store_dwordx4 v17, v[88:91], s[98:99]
	global_store_dwordx4 v18, v[92:95], s[98:99]
	global_store_dwordx4 v19, v[96:99], s[98:99]
	s_waitcnt vmcnt(23)
	ds_write_b32 v14, v100 offset:0
	ds_write_b32 v14, v101 offset:4
	ds_write_b32 v14, v102 offset:8
	ds_write_b32 v14, v103 offset:12
	s_waitcnt vmcnt(22)
	ds_write_b32 v14, v104 offset:1056
	ds_write_b32 v14, v105 offset:1060
	ds_write_b32 v14, v106 offset:1064
	ds_write_b32 v14, v107 offset:1068
	s_waitcnt vmcnt(21)
	ds_write_b32 v14, v108 offset:2112
	ds_write_b32 v14, v109 offset:2116
	ds_write_b32 v14, v110 offset:2120
	ds_write_b32 v14, v111 offset:2124
	s_waitcnt vmcnt(20)
	ds_write_b32 v14, v112 offset:3168
	ds_write_b32 v14, v113 offset:3172
	ds_write_b32 v14, v114 offset:3176
	ds_write_b32 v14, v115 offset:3180
	s_waitcnt vmcnt(19)
	ds_write_b32 v14, v116 offset:4224
	ds_write_b32 v14, v117 offset:4228
	ds_write_b32 v14, v118 offset:4232
	ds_write_b32 v14, v119 offset:4236
	s_waitcnt vmcnt(18)
	ds_write_b32 v14, v120 offset:5280
	ds_write_b32 v14, v121 offset:5284
	ds_write_b32 v14, v122 offset:5288
	ds_write_b32 v14, v123 offset:5292
	s_waitcnt vmcnt(17)
	ds_write_b32 v14, v124 offset:6336
	ds_write_b32 v14, v125 offset:6340
	ds_write_b32 v14, v126 offset:6344
	ds_write_b32 v14, v127 offset:6348
	s_waitcnt vmcnt(16)
	ds_write_b32 v14, v128 offset:7392
	ds_write_b32 v14, v129 offset:7396
	ds_write_b32 v14, v130 offset:7400
	ds_write_b32 v14, v131 offset:7404
	s_add_u32 s95, s94, 0x3c00
	s_lshr_b32 vcc_lo, s95, 7
	s_and_b32 vcc_hi, s95, 0x7f
	s_lshl_b32 vcc_lo, vcc_lo, 20
	s_lshl_b32 vcc_hi, vcc_hi, 7
	s_add_u32 s96, s100, vcc_lo
	s_addc_u32 s97, s101, 0
	s_add_u32 s96, s96, vcc_hi
	s_addc_u32 s97, s97, 0
	global_load_dwordx4 v[100:103], v6, s[96:97]
	global_load_dwordx4 v[104:107], v7, s[96:97]
	global_load_dwordx4 v[108:111], v8, s[96:97]
	global_load_dwordx4 v[112:115], v9, s[96:97]
	global_load_dwordx4 v[116:119], v10, s[96:97]
	global_load_dwordx4 v[120:123], v11, s[96:97]
	global_load_dwordx4 v[124:127], v12, s[96:97]
	global_load_dwordx4 v[128:131], v13, s[96:97]
	ds_read2_b32 v[52:53], v15 offset0:0 offset1:33
	ds_read2_b32 v[54:55], v15 offset0:66 offset1:99
	ds_read2_b32 v[56:57], v15 offset0:132 offset1:165
	ds_read2_b32 v[58:59], v15 offset0:198 offset1:231
	ds_read2_b32 v[60:61], v15 offset0:8 offset1:41
	ds_read2_b32 v[62:63], v15 offset0:74 offset1:107
	ds_read2_b32 v[64:65], v15 offset0:140 offset1:173
	ds_read2_b32 v[66:67], v15 offset0:206 offset1:239
	ds_read2_b32 v[68:69], v15 offset0:16 offset1:49
	ds_read2_b32 v[70:71], v15 offset0:82 offset1:115
	ds_read2_b32 v[72:73], v15 offset0:148 offset1:181
	ds_read2_b32 v[74:75], v15 offset0:214 offset1:247
	ds_read2_b32 v[76:77], v15 offset0:24 offset1:57
	ds_read2_b32 v[78:79], v15 offset0:90 offset1:123
	ds_read2_b32 v[80:81], v15 offset0:156 offset1:189
	ds_read2_b32 v[82:83], v15 offset0:222 offset1:255
	s_add_u32 s95, s94, 0x3400
	s_lshr_b32 vcc_lo, s95, 7
	s_and_b32 vcc_hi, s95, 0x7f
	s_mul_i32 vcc_hi, vcc_hi, 0xac000
	s_lshl_b32 vcc_lo, vcc_lo, 7
	s_add_u32 s98, s66, 0x12d00000
	s_addc_u32 s99, s67, 0
	s_add_u32 s98, s98, vcc_hi
	s_addc_u32 s99, s99, 0
	s_add_u32 s98, s98, vcc_lo
	s_addc_u32 s99, s99, 0
	s_waitcnt lgkmcnt(0)
	v_cvt_pk_bf16_f32 v84, v52, v53
	v_cvt_pk_bf16_f32 v85, v54, v55
	v_cvt_pk_bf16_f32 v86, v56, v57
	v_cvt_pk_bf16_f32 v87, v58, v59
	v_cvt_pk_bf16_f32 v88, v60, v61
	v_cvt_pk_bf16_f32 v89, v62, v63
	v_cvt_pk_bf16_f32 v90, v64, v65
	v_cvt_pk_bf16_f32 v91, v66, v67
	v_cvt_pk_bf16_f32 v92, v68, v69
	v_cvt_pk_bf16_f32 v93, v70, v71
	v_cvt_pk_bf16_f32 v94, v72, v73
	v_cvt_pk_bf16_f32 v95, v74, v75
	v_cvt_pk_bf16_f32 v96, v76, v77
	v_cvt_pk_bf16_f32 v97, v78, v79
	v_cvt_pk_bf16_f32 v98, v80, v81
	v_cvt_pk_bf16_f32 v99, v82, v83
	global_store_dwordx4 v16, v[84:87], s[98:99]
	global_store_dwordx4 v17, v[88:91], s[98:99]
	global_store_dwordx4 v18, v[92:95], s[98:99]
	global_store_dwordx4 v19, v[96:99], s[98:99]
	s_waitcnt vmcnt(23)
	ds_write_b32 v14, v20 offset:0
	ds_write_b32 v14, v21 offset:4
	ds_write_b32 v14, v22 offset:8
	ds_write_b32 v14, v23 offset:12
	s_waitcnt vmcnt(22)
	ds_write_b32 v14, v24 offset:1056
	ds_write_b32 v14, v25 offset:1060
	ds_write_b32 v14, v26 offset:1064
	ds_write_b32 v14, v27 offset:1068
	s_waitcnt vmcnt(21)
	ds_write_b32 v14, v28 offset:2112
	ds_write_b32 v14, v29 offset:2116
	ds_write_b32 v14, v30 offset:2120
	ds_write_b32 v14, v31 offset:2124
	s_waitcnt vmcnt(20)
	ds_write_b32 v14, v32 offset:3168
	ds_write_b32 v14, v33 offset:3172
	ds_write_b32 v14, v34 offset:3176
	ds_write_b32 v14, v35 offset:3180
	s_waitcnt vmcnt(19)
	ds_write_b32 v14, v36 offset:4224
	ds_write_b32 v14, v37 offset:4228
	ds_write_b32 v14, v38 offset:4232
	ds_write_b32 v14, v39 offset:4236
	s_waitcnt vmcnt(18)
	ds_write_b32 v14, v40 offset:5280
	ds_write_b32 v14, v41 offset:5284
	ds_write_b32 v14, v42 offset:5288
	ds_write_b32 v14, v43 offset:5292
	s_waitcnt vmcnt(17)
	ds_write_b32 v14, v44 offset:6336
	ds_write_b32 v14, v45 offset:6340
	ds_write_b32 v14, v46 offset:6344
	ds_write_b32 v14, v47 offset:6348
	s_waitcnt vmcnt(16)
	ds_write_b32 v14, v48 offset:7392
	ds_write_b32 v14, v49 offset:7396
	ds_write_b32 v14, v50 offset:7400
	ds_write_b32 v14, v51 offset:7404
	ds_read2_b32 v[52:53], v15 offset0:0 offset1:33
	ds_read2_b32 v[54:55], v15 offset0:66 offset1:99
	ds_read2_b32 v[56:57], v15 offset0:132 offset1:165
	ds_read2_b32 v[58:59], v15 offset0:198 offset1:231
	ds_read2_b32 v[60:61], v15 offset0:8 offset1:41
	ds_read2_b32 v[62:63], v15 offset0:74 offset1:107
	ds_read2_b32 v[64:65], v15 offset0:140 offset1:173
	ds_read2_b32 v[66:67], v15 offset0:206 offset1:239
	ds_read2_b32 v[68:69], v15 offset0:16 offset1:49
	ds_read2_b32 v[70:71], v15 offset0:82 offset1:115
	ds_read2_b32 v[72:73], v15 offset0:148 offset1:181
	ds_read2_b32 v[74:75], v15 offset0:214 offset1:247
	ds_read2_b32 v[76:77], v15 offset0:24 offset1:57
	ds_read2_b32 v[78:79], v15 offset0:90 offset1:123
	ds_read2_b32 v[80:81], v15 offset0:156 offset1:189
	ds_read2_b32 v[82:83], v15 offset0:222 offset1:255
	s_add_u32 s95, s94, 0x3800
	s_lshr_b32 vcc_lo, s95, 7
	s_and_b32 vcc_hi, s95, 0x7f
	s_mul_i32 vcc_hi, vcc_hi, 0xac000
	s_lshl_b32 vcc_lo, vcc_lo, 7
	s_add_u32 s98, s66, 0x12d00000
	s_addc_u32 s99, s67, 0
	s_add_u32 s98, s98, vcc_hi
	s_addc_u32 s99, s99, 0
	s_add_u32 s98, s98, vcc_lo
	s_addc_u32 s99, s99, 0
	s_waitcnt lgkmcnt(0)
	v_cvt_pk_bf16_f32 v84, v52, v53
	v_cvt_pk_bf16_f32 v85, v54, v55
	v_cvt_pk_bf16_f32 v86, v56, v57
	v_cvt_pk_bf16_f32 v87, v58, v59
	v_cvt_pk_bf16_f32 v88, v60, v61
	v_cvt_pk_bf16_f32 v89, v62, v63
	v_cvt_pk_bf16_f32 v90, v64, v65
	v_cvt_pk_bf16_f32 v91, v66, v67
	v_cvt_pk_bf16_f32 v92, v68, v69
	v_cvt_pk_bf16_f32 v93, v70, v71
	v_cvt_pk_bf16_f32 v94, v72, v73
	v_cvt_pk_bf16_f32 v95, v74, v75
	v_cvt_pk_bf16_f32 v96, v76, v77
	v_cvt_pk_bf16_f32 v97, v78, v79
	v_cvt_pk_bf16_f32 v98, v80, v81
	v_cvt_pk_bf16_f32 v99, v82, v83
	global_store_dwordx4 v16, v[84:87], s[98:99]
	global_store_dwordx4 v17, v[88:91], s[98:99]
	global_store_dwordx4 v18, v[92:95], s[98:99]
	global_store_dwordx4 v19, v[96:99], s[98:99]
	s_waitcnt vmcnt(15)
	ds_write_b32 v14, v100 offset:0
	ds_write_b32 v14, v101 offset:4
	ds_write_b32 v14, v102 offset:8
	ds_write_b32 v14, v103 offset:12
	s_waitcnt vmcnt(14)
	ds_write_b32 v14, v104 offset:1056
	ds_write_b32 v14, v105 offset:1060
	ds_write_b32 v14, v106 offset:1064
	ds_write_b32 v14, v107 offset:1068
	s_waitcnt vmcnt(13)
	ds_write_b32 v14, v108 offset:2112
	ds_write_b32 v14, v109 offset:2116
	ds_write_b32 v14, v110 offset:2120
	ds_write_b32 v14, v111 offset:2124
	s_waitcnt vmcnt(12)
	ds_write_b32 v14, v112 offset:3168
	ds_write_b32 v14, v113 offset:3172
	ds_write_b32 v14, v114 offset:3176
	ds_write_b32 v14, v115 offset:3180
	s_waitcnt vmcnt(11)
	ds_write_b32 v14, v116 offset:4224
	ds_write_b32 v14, v117 offset:4228
	ds_write_b32 v14, v118 offset:4232
	ds_write_b32 v14, v119 offset:4236
	s_waitcnt vmcnt(10)
	ds_write_b32 v14, v120 offset:5280
	ds_write_b32 v14, v121 offset:5284
	ds_write_b32 v14, v122 offset:5288
	ds_write_b32 v14, v123 offset:5292
	s_waitcnt vmcnt(9)
	ds_write_b32 v14, v124 offset:6336
	ds_write_b32 v14, v125 offset:6340
	ds_write_b32 v14, v126 offset:6344
	ds_write_b32 v14, v127 offset:6348
	s_waitcnt vmcnt(8)
	ds_write_b32 v14, v128 offset:7392
	ds_write_b32 v14, v129 offset:7396
	ds_write_b32 v14, v130 offset:7400
	ds_write_b32 v14, v131 offset:7404
	ds_read2_b32 v[52:53], v15 offset0:0 offset1:33
	ds_read2_b32 v[54:55], v15 offset0:66 offset1:99
	ds_read2_b32 v[56:57], v15 offset0:132 offset1:165
	ds_read2_b32 v[58:59], v15 offset0:198 offset1:231
	ds_read2_b32 v[60:61], v15 offset0:8 offset1:41
	ds_read2_b32 v[62:63], v15 offset0:74 offset1:107
	ds_read2_b32 v[64:65], v15 offset0:140 offset1:173
	ds_read2_b32 v[66:67], v15 offset0:206 offset1:239
	ds_read2_b32 v[68:69], v15 offset0:16 offset1:49
	ds_read2_b32 v[70:71], v15 offset0:82 offset1:115
	ds_read2_b32 v[72:73], v15 offset0:148 offset1:181
	ds_read2_b32 v[74:75], v15 offset0:214 offset1:247
	ds_read2_b32 v[76:77], v15 offset0:24 offset1:57
	ds_read2_b32 v[78:79], v15 offset0:90 offset1:123
	ds_read2_b32 v[80:81], v15 offset0:156 offset1:189
	ds_read2_b32 v[82:83], v15 offset0:222 offset1:255
	s_add_u32 s95, s94, 0x3c00
	s_lshr_b32 vcc_lo, s95, 7
	s_and_b32 vcc_hi, s95, 0x7f
	s_mul_i32 vcc_hi, vcc_hi, 0xac000
	s_lshl_b32 vcc_lo, vcc_lo, 7
	s_add_u32 s98, s66, 0x12d00000
	s_addc_u32 s99, s67, 0
	s_add_u32 s98, s98, vcc_hi
	s_addc_u32 s99, s99, 0
	s_add_u32 s98, s98, vcc_lo
	s_addc_u32 s99, s99, 0
	s_waitcnt lgkmcnt(0)
	v_cvt_pk_bf16_f32 v84, v52, v53
	v_cvt_pk_bf16_f32 v85, v54, v55
	v_cvt_pk_bf16_f32 v86, v56, v57
	v_cvt_pk_bf16_f32 v87, v58, v59
	v_cvt_pk_bf16_f32 v88, v60, v61
	v_cvt_pk_bf16_f32 v89, v62, v63
	v_cvt_pk_bf16_f32 v90, v64, v65
	v_cvt_pk_bf16_f32 v91, v66, v67
	v_cvt_pk_bf16_f32 v92, v68, v69
	v_cvt_pk_bf16_f32 v93, v70, v71
	v_cvt_pk_bf16_f32 v94, v72, v73
	v_cvt_pk_bf16_f32 v95, v74, v75
	v_cvt_pk_bf16_f32 v96, v76, v77
	v_cvt_pk_bf16_f32 v97, v78, v79
	v_cvt_pk_bf16_f32 v98, v80, v81
	v_cvt_pk_bf16_f32 v99, v82, v83
	global_store_dwordx4 v16, v[84:87], s[98:99]
	global_store_dwordx4 v17, v[88:91], s[98:99]
	global_store_dwordx4 v18, v[92:95], s[98:99]
	global_store_dwordx4 v19, v[96:99], s[98:99]
